# peeled first K-iteration in 6 persistent GEMM loops (first-touch MFMA with SrcC=0), removed 128 v_mov accumulator zeroing per tile
# speedup vs baseline: 1.0092x; 1.0035x over previous
.LBB0_273:
	s_xor_b64 s[34:35], s[6:7], -1
	s_and_b64 s[6:7], s[6:7], exec
	s_cselect_b32 s11, s13, s3
	s_cselect_b32 s15, s12, s2
	s_cselect_b32 s36, s17, s5
	s_cselect_b32 s37, s16, s4
	s_add_u32 s2, s2, 0x40080
	s_addc_u32 s3, s3, 0
	s_add_u32 s38, s4, 0x100
	s_addc_u32 s39, s5, 0
	s_mov_b32 s69, -2
	s_waitcnt lgkmcnt(0)
	ds_read_b128 v[128:131], v211
	ds_read_b128 v[132:135], v211 offset:1024
	ds_read_b128 v[136:139], v211 offset:2048
	ds_read_b128 v[140:143], v211 offset:3072
	s_add_u32 s4, s2, 0xfffc0080
	s_addc_u32 s5, s3, -1
	s_cmp_eq_u32 s69, 12
	s_cselect_b32 s7, s11, s5
	s_cselect_b32 s6, s15, s4
	s_cselect_b32 s5, s36, s39
	s_cselect_b32 s4, s37, s38
	v_lshl_add_u64 v[200:201], s[2:3], 0, v[162:163]
	s_add_i32 m0, s44, 0xc000
	ds_read_b128 v[168:171], v212
	ds_read_b128 v[172:175], v212 offset:1024
	ds_read_b128 v[176:179], v212 offset:2048
	ds_read_b128 v[180:183], v212 offset:3072
	ds_read_b128 v[184:187], v212 offset:4096
	ds_read_b128 v[188:191], v212 offset:5120
	ds_read_b128 v[192:195], v212 offset:6144
	ds_read_b128 v[196:199], v212 offset:7168
	global_load_lds_dwordx4 v[200:201], off
	v_lshl_add_u64 v[200:201], s[2:3], 0, v[164:165]
	s_add_i32 m0, s44, 0xe000
	s_nop 0
	global_load_lds_dwordx4 v[200:201], off
	ds_read_b128 v[222:225], v213
	ds_read_b128 v[226:229], v213 offset:1024
	ds_read_b128 v[230:233], v213 offset:2048
	ds_read_b128 v[234:237], v213 offset:3072
	s_waitcnt lgkmcnt(0)
	s_waitcnt vmcnt(8)
	s_barrier
	s_setprio 1
	v_mfma_f32_16x16x32_bf16 v[124:127], v[128:131], v[168:171], 0
	v_mfma_f32_16x16x32_bf16 v[120:123], v[136:139], v[168:171], 0
	v_mfma_f32_16x16x32_bf16 v[108:111], v[128:131], v[176:179], 0
	v_mfma_f32_16x16x32_bf16 v[104:107], v[136:139], v[176:179], 0
	v_mfma_f32_16x16x32_bf16 v[92:95], v[128:131], v[184:187], 0
	v_mfma_f32_16x16x32_bf16 v[88:91], v[136:139], v[184:187], 0
	v_mfma_f32_16x16x32_bf16 v[76:79], v[128:131], v[192:195], 0
	v_mfma_f32_16x16x32_bf16 v[72:75], v[136:139], v[192:195], 0
	v_mfma_f32_16x16x32_bf16 v[124:127], v[132:135], v[172:175], v[124:127]
	v_mfma_f32_16x16x32_bf16 v[120:123], v[140:143], v[172:175], v[120:123]
	v_mfma_f32_16x16x32_bf16 v[108:111], v[132:135], v[180:183], v[108:111]
	v_mfma_f32_16x16x32_bf16 v[104:107], v[140:143], v[180:183], v[104:107]
	v_mfma_f32_16x16x32_bf16 v[92:95], v[132:135], v[188:191], v[92:95]
	v_mfma_f32_16x16x32_bf16 v[88:91], v[140:143], v[188:191], v[88:91]
	v_mfma_f32_16x16x32_bf16 v[76:79], v[132:135], v[196:199], v[76:79]
	v_mfma_f32_16x16x32_bf16 v[72:75], v[140:143], v[196:199], v[72:75]
	v_mfma_f32_16x16x32_bf16 v[116:119], v[222:225], v[168:171], 0
	v_mfma_f32_16x16x32_bf16 v[112:115], v[230:233], v[168:171], 0
	v_mfma_f32_16x16x32_bf16 v[100:103], v[222:225], v[176:179], 0
	v_mfma_f32_16x16x32_bf16 v[96:99], v[230:233], v[176:179], 0
	v_mfma_f32_16x16x32_bf16 v[84:87], v[222:225], v[184:187], 0
	v_mfma_f32_16x16x32_bf16 v[80:83], v[230:233], v[184:187], 0
	v_mfma_f32_16x16x32_bf16 v[68:71], v[222:225], v[192:195], 0
	v_mfma_f32_16x16x32_bf16 v[64:67], v[230:233], v[192:195], 0
	v_mfma_f32_16x16x32_bf16 v[116:119], v[226:229], v[172:175], v[116:119]
	v_mfma_f32_16x16x32_bf16 v[112:115], v[234:237], v[172:175], v[112:115]
	v_mfma_f32_16x16x32_bf16 v[100:103], v[226:229], v[180:183], v[100:103]
	v_mfma_f32_16x16x32_bf16 v[96:99], v[234:237], v[180:183], v[96:99]
	v_mfma_f32_16x16x32_bf16 v[84:87], v[226:229], v[188:191], v[84:87]
	v_mfma_f32_16x16x32_bf16 v[80:83], v[234:237], v[188:191], v[80:83]
	v_mfma_f32_16x16x32_bf16 v[68:71], v[226:229], v[196:199], v[68:71]
	v_mfma_f32_16x16x32_bf16 v[64:67], v[234:237], v[196:199], v[64:67]
	s_setprio 0
	s_barrier
	ds_read_b128 v[168:171], v212 offset:16384
	ds_read_b128 v[172:175], v212 offset:17408
	ds_read_b128 v[176:179], v212 offset:18432
	ds_read_b128 v[180:183], v212 offset:19456
	ds_read_b128 v[184:187], v212 offset:20480
	ds_read_b128 v[188:191], v212 offset:21504
	ds_read_b128 v[192:195], v212 offset:22528
	ds_read_b128 v[196:199], v212 offset:23552
	s_mov_b32 m0, s42
	v_lshl_add_u64 v[200:201], s[4:5], 0, v[144:145]
	global_load_lds_dwordx4 v[200:201], off
	v_lshl_add_u64 v[238:239], s[4:5], 0, v[146:147]
	s_mov_b32 m0, s43
	s_nop 0
	global_load_lds_dwordx4 v[238:239], off
	s_mov_b32 m0, s44
	v_lshl_add_u64 v[240:241], s[6:7], 0, v[144:145]
	global_load_lds_dwordx4 v[240:241], off
	v_lshl_add_u64 v[242:243], s[6:7], 0, v[146:147]
	s_mov_b32 m0, s45
	s_nop 0
	global_load_lds_dwordx4 v[242:243], off
	s_add_u32 s70, s4, 0x40000
	s_addc_u32 s71, s5, 0
	s_mov_b32 m0, s46
	v_lshl_add_u64 v[248:249], s[70:71], 0, v[144:145]
	global_load_lds_dwordx4 v[248:249], off
	v_lshl_add_u64 v[248:249], s[70:71], 0, v[146:147]
	s_mov_b32 m0, s47
	s_nop 0
	global_load_lds_dwordx4 v[248:249], off
	s_waitcnt lgkmcnt(0)
	s_waitcnt vmcnt(8)
	s_barrier
	s_setprio 1
	v_mfma_f32_16x16x32_bf16 v[60:63], v[128:131], v[168:171], 0
	v_mfma_f32_16x16x32_bf16 v[56:59], v[136:139], v[168:171], 0
	v_mfma_f32_16x16x32_bf16 v[44:47], v[128:131], v[176:179], 0
	v_mfma_f32_16x16x32_bf16 v[40:43], v[136:139], v[176:179], 0
	v_mfma_f32_16x16x32_bf16 v[28:31], v[128:131], v[184:187], 0
	v_mfma_f32_16x16x32_bf16 v[24:27], v[136:139], v[184:187], 0
	v_mfma_f32_16x16x32_bf16 v[12:15], v[128:131], v[192:195], 0
	v_mfma_f32_16x16x32_bf16 v[8:11], v[136:139], v[192:195], 0
	v_mfma_f32_16x16x32_bf16 v[60:63], v[132:135], v[172:175], v[60:63]
	v_mfma_f32_16x16x32_bf16 v[56:59], v[140:143], v[172:175], v[56:59]
	v_mfma_f32_16x16x32_bf16 v[44:47], v[132:135], v[180:183], v[44:47]
	v_mfma_f32_16x16x32_bf16 v[40:43], v[140:143], v[180:183], v[40:43]
	v_mfma_f32_16x16x32_bf16 v[28:31], v[132:135], v[188:191], v[28:31]
	v_mfma_f32_16x16x32_bf16 v[24:27], v[140:143], v[188:191], v[24:27]
	v_mfma_f32_16x16x32_bf16 v[12:15], v[132:135], v[196:199], v[12:15]
	v_mfma_f32_16x16x32_bf16 v[8:11], v[140:143], v[196:199], v[8:11]
	v_mfma_f32_16x16x32_bf16 v[52:55], v[222:225], v[168:171], 0
	v_mfma_f32_16x16x32_bf16 v[48:51], v[230:233], v[168:171], 0
	v_mfma_f32_16x16x32_bf16 v[36:39], v[222:225], v[176:179], 0
	v_mfma_f32_16x16x32_bf16 v[32:35], v[230:233], v[176:179], 0
	v_mfma_f32_16x16x32_bf16 v[20:23], v[222:225], v[184:187], 0
	v_mfma_f32_16x16x32_bf16 v[16:19], v[230:233], v[184:187], 0
	v_mfma_f32_16x16x32_bf16 v[4:7], v[222:225], v[192:195], 0
	v_mfma_f32_16x16x32_bf16 v[0:3], v[230:233], v[192:195], 0
	v_mfma_f32_16x16x32_bf16 v[52:55], v[226:229], v[172:175], v[52:55]
	v_mfma_f32_16x16x32_bf16 v[48:51], v[234:237], v[172:175], v[48:51]
	v_mfma_f32_16x16x32_bf16 v[36:39], v[226:229], v[180:183], v[36:39]
	v_mfma_f32_16x16x32_bf16 v[32:35], v[234:237], v[180:183], v[32:35]
	v_mfma_f32_16x16x32_bf16 v[20:23], v[226:229], v[188:191], v[20:23]
	v_mfma_f32_16x16x32_bf16 v[16:19], v[234:237], v[188:191], v[16:19]
	v_mfma_f32_16x16x32_bf16 v[4:7], v[226:229], v[196:199], v[4:7]
	v_mfma_f32_16x16x32_bf16 v[0:3], v[234:237], v[196:199], v[0:3]
	s_setprio 0
	s_barrier
	ds_read_b128 v[128:131], v214
	ds_read_b128 v[132:135], v214 offset:1024
	ds_read_b128 v[136:139], v214 offset:2048
	ds_read_b128 v[140:143], v214 offset:3072
	s_add_u32 s6, s6, 0x40000
	s_addc_u32 s7, s7, 0
	s_mov_b32 m0, s48
	v_lshl_add_u64 v[222:223], s[6:7], 0, v[144:145]
	ds_read_b128 v[168:171], v212 offset:32768
	ds_read_b128 v[172:175], v212 offset:33792
	ds_read_b128 v[176:179], v212 offset:34816
	ds_read_b128 v[180:183], v212 offset:35840
	ds_read_b128 v[184:187], v212 offset:36864
	ds_read_b128 v[188:191], v212 offset:37888
	ds_read_b128 v[192:195], v212 offset:38912
	ds_read_b128 v[196:199], v212 offset:39936
	global_load_lds_dwordx4 v[222:223], off
	v_lshl_add_u64 v[222:223], s[6:7], 0, v[146:147]
	s_mov_b32 m0, s49
	s_nop 0
	global_load_lds_dwordx4 v[222:223], off
	ds_read_b128 v[222:225], v215
	ds_read_b128 v[226:229], v215 offset:1024
	ds_read_b128 v[230:233], v215 offset:2048
	ds_read_b128 v[234:237], v215 offset:3072
	s_waitcnt lgkmcnt(0)
	s_waitcnt vmcnt(8)
	s_barrier
	s_setprio 1
	v_mfma_f32_16x16x32_bf16 v[124:127], v[128:131], v[168:171], v[124:127]
	v_mfma_f32_16x16x32_bf16 v[120:123], v[136:139], v[168:171], v[120:123]
	v_mfma_f32_16x16x32_bf16 v[108:111], v[128:131], v[176:179], v[108:111]
	v_mfma_f32_16x16x32_bf16 v[104:107], v[136:139], v[176:179], v[104:107]
	v_mfma_f32_16x16x32_bf16 v[92:95], v[128:131], v[184:187], v[92:95]
	v_mfma_f32_16x16x32_bf16 v[88:91], v[136:139], v[184:187], v[88:91]
	v_mfma_f32_16x16x32_bf16 v[76:79], v[128:131], v[192:195], v[76:79]
	v_mfma_f32_16x16x32_bf16 v[72:75], v[136:139], v[192:195], v[72:75]
	v_mfma_f32_16x16x32_bf16 v[124:127], v[132:135], v[172:175], v[124:127]
	v_mfma_f32_16x16x32_bf16 v[120:123], v[140:143], v[172:175], v[120:123]
	v_mfma_f32_16x16x32_bf16 v[108:111], v[132:135], v[180:183], v[108:111]
	v_mfma_f32_16x16x32_bf16 v[104:107], v[140:143], v[180:183], v[104:107]
	v_mfma_f32_16x16x32_bf16 v[92:95], v[132:135], v[188:191], v[92:95]
	v_mfma_f32_16x16x32_bf16 v[88:91], v[140:143], v[188:191], v[88:91]
	v_mfma_f32_16x16x32_bf16 v[76:79], v[132:135], v[196:199], v[76:79]
	v_mfma_f32_16x16x32_bf16 v[72:75], v[140:143], v[196:199], v[72:75]
	v_mfma_f32_16x16x32_bf16 v[116:119], v[222:225], v[168:171], v[116:119]
	v_mfma_f32_16x16x32_bf16 v[112:115], v[230:233], v[168:171], v[112:115]
	v_mfma_f32_16x16x32_bf16 v[100:103], v[222:225], v[176:179], v[100:103]
	v_mfma_f32_16x16x32_bf16 v[96:99], v[230:233], v[176:179], v[96:99]
	v_mfma_f32_16x16x32_bf16 v[84:87], v[222:225], v[184:187], v[84:87]
	v_mfma_f32_16x16x32_bf16 v[80:83], v[230:233], v[184:187], v[80:83]
	v_mfma_f32_16x16x32_bf16 v[68:71], v[222:225], v[192:195], v[68:71]
	v_mfma_f32_16x16x32_bf16 v[64:67], v[230:233], v[192:195], v[64:67]
	v_mfma_f32_16x16x32_bf16 v[116:119], v[226:229], v[172:175], v[116:119]
	v_mfma_f32_16x16x32_bf16 v[112:115], v[234:237], v[172:175], v[112:115]
	v_mfma_f32_16x16x32_bf16 v[100:103], v[226:229], v[180:183], v[100:103]
	v_mfma_f32_16x16x32_bf16 v[96:99], v[234:237], v[180:183], v[96:99]
	v_mfma_f32_16x16x32_bf16 v[84:87], v[226:229], v[188:191], v[84:87]
	v_mfma_f32_16x16x32_bf16 v[80:83], v[234:237], v[188:191], v[80:83]
	v_mfma_f32_16x16x32_bf16 v[68:71], v[226:229], v[196:199], v[68:71]
	v_mfma_f32_16x16x32_bf16 v[64:67], v[234:237], v[196:199], v[64:67]
	s_setprio 0
	s_barrier
	ds_read_b128 v[168:171], v212 offset:49152
	ds_read_b128 v[172:175], v212 offset:50176
	ds_read_b128 v[176:179], v212 offset:51200
	ds_read_b128 v[180:183], v212 offset:52224
	ds_read_b128 v[184:187], v212 offset:53248
	ds_read_b128 v[188:191], v212 offset:54272
	ds_read_b128 v[192:195], v212 offset:55296
	ds_read_b128 v[196:199], v212 offset:56320
	s_mov_b32 m0, s51
	v_lshl_add_u64 v[200:201], v[200:201], 0, s[18:19]
	global_load_lds_dwordx4 v[200:201], off
	v_lshl_add_u64 v[200:201], v[238:239], 0, s[18:19]
	s_mov_b32 m0, s52
	s_nop 0
	global_load_lds_dwordx4 v[200:201], off
	s_mov_b32 m0, s54
	v_lshl_add_u64 v[200:201], v[240:241], 0, s[18:19]
	global_load_lds_dwordx4 v[200:201], off
	v_lshl_add_u64 v[200:201], v[242:243], 0, s[18:19]
	s_mov_b32 m0, s55
	s_nop 0
	global_load_lds_dwordx4 v[200:201], off
	s_add_u32 s4, s4, 0x40080
	s_addc_u32 s5, s5, 0
	s_mov_b32 m0, s56
	v_lshl_add_u64 v[248:249], s[4:5], 0, v[144:145]
	global_load_lds_dwordx4 v[248:249], off
	v_lshl_add_u64 v[248:249], s[4:5], 0, v[146:147]
	s_mov_b32 m0, s57
	s_nop 0
	global_load_lds_dwordx4 v[248:249], off
	s_waitcnt lgkmcnt(0)
	s_waitcnt vmcnt(8)
	s_barrier
	s_setprio 1
	v_mfma_f32_16x16x32_bf16 v[60:63], v[128:131], v[168:171], v[60:63]
	v_mfma_f32_16x16x32_bf16 v[56:59], v[136:139], v[168:171], v[56:59]
	v_mfma_f32_16x16x32_bf16 v[44:47], v[128:131], v[176:179], v[44:47]
	v_mfma_f32_16x16x32_bf16 v[40:43], v[136:139], v[176:179], v[40:43]
	v_mfma_f32_16x16x32_bf16 v[28:31], v[128:131], v[184:187], v[28:31]
	v_mfma_f32_16x16x32_bf16 v[24:27], v[136:139], v[184:187], v[24:27]
	v_mfma_f32_16x16x32_bf16 v[12:15], v[128:131], v[192:195], v[12:15]
	v_mfma_f32_16x16x32_bf16 v[8:11], v[136:139], v[192:195], v[8:11]
	v_mfma_f32_16x16x32_bf16 v[60:63], v[132:135], v[172:175], v[60:63]
	v_mfma_f32_16x16x32_bf16 v[56:59], v[140:143], v[172:175], v[56:59]
	v_mfma_f32_16x16x32_bf16 v[44:47], v[132:135], v[180:183], v[44:47]
	v_mfma_f32_16x16x32_bf16 v[40:43], v[140:143], v[180:183], v[40:43]
	v_mfma_f32_16x16x32_bf16 v[28:31], v[132:135], v[188:191], v[28:31]
	v_mfma_f32_16x16x32_bf16 v[24:27], v[140:143], v[188:191], v[24:27]
	v_mfma_f32_16x16x32_bf16 v[12:15], v[132:135], v[196:199], v[12:15]
	v_mfma_f32_16x16x32_bf16 v[8:11], v[140:143], v[196:199], v[8:11]
	v_mfma_f32_16x16x32_bf16 v[52:55], v[222:225], v[168:171], v[52:55]
	v_mfma_f32_16x16x32_bf16 v[48:51], v[230:233], v[168:171], v[48:51]
	v_mfma_f32_16x16x32_bf16 v[36:39], v[222:225], v[176:179], v[36:39]
	v_mfma_f32_16x16x32_bf16 v[32:35], v[230:233], v[176:179], v[32:35]
	v_mfma_f32_16x16x32_bf16 v[20:23], v[222:225], v[184:187], v[20:23]
	v_mfma_f32_16x16x32_bf16 v[16:19], v[230:233], v[184:187], v[16:19]
	v_mfma_f32_16x16x32_bf16 v[4:7], v[222:225], v[192:195], v[4:7]
	v_mfma_f32_16x16x32_bf16 v[0:3], v[230:233], v[192:195], v[0:3]
	v_mfma_f32_16x16x32_bf16 v[52:55], v[226:229], v[172:175], v[52:55]
	v_mfma_f32_16x16x32_bf16 v[48:51], v[234:237], v[172:175], v[48:51]
	v_mfma_f32_16x16x32_bf16 v[36:39], v[226:229], v[180:183], v[36:39]
	v_mfma_f32_16x16x32_bf16 v[32:35], v[234:237], v[180:183], v[32:35]
	v_mfma_f32_16x16x32_bf16 v[20:23], v[226:229], v[188:191], v[20:23]
	v_mfma_f32_16x16x32_bf16 v[16:19], v[234:237], v[188:191], v[16:19]
	v_mfma_f32_16x16x32_bf16 v[4:7], v[226:229], v[196:199], v[4:7]
	v_mfma_f32_16x16x32_bf16 v[0:3], v[234:237], v[196:199], v[0:3]
	s_setprio 0
	s_add_i32 s69, s69, 2
	s_add_u32 s2, s2, 0x100
	s_addc_u32 s3, s3, 0
	s_add_u32 s38, s38, 0x100
	s_addc_u32 s39, s39, 0
	s_cmp_gt_u32 s69, 13
	s_barrier

.LBB0_882:
	s_xor_b64 s[18:19], s[36:37], -1
	s_and_b64 s[30:31], s[36:37], exec
	s_cselect_b32 s25, s15, s27
	s_cselect_b32 s34, s14, s26
	s_cselect_b32 s36, s17, s29
	s_cselect_b32 s37, s16, s28
	s_add_u32 s26, s26, 0x40080
	s_addc_u32 s27, s27, 0
	s_add_u32 s38, s28, 0x100
	s_addc_u32 s39, s29, 0
	s_mov_b32 s40, -2
	s_waitcnt lgkmcnt(0)
	ds_read_b128 v[128:131], v186
	ds_read_b128 v[132:135], v186 offset:1024
	ds_read_b128 v[136:139], v186 offset:2048
	ds_read_b128 v[140:143], v186 offset:3072
	s_add_u32 s28, s26, 0xfffc0080
	s_addc_u32 s29, s27, -1
	s_cmp_eq_u32 s40, 12
	s_cselect_b32 s31, s25, s29
	s_cselect_b32 s30, s34, s28
	s_cselect_b32 s29, s36, s39
	s_cselect_b32 s28, s37, s38
	v_lshl_add_u64 v[182:183], s[26:27], 0, v[164:165]
	s_add_i32 m0, s45, 0xc000
	ds_read_b128 v[144:147], v187
	ds_read_b128 v[148:151], v187 offset:1024
	ds_read_b128 v[152:155], v187 offset:2048
	ds_read_b128 v[156:159], v187 offset:3072
	ds_read_b128 v[170:173], v187 offset:4096
	ds_read_b128 v[174:177], v187 offset:5120
	ds_read_b128 v[178:181], v187 offset:6144
	ds_read_b128 v[192:195], v187 offset:7168
	global_load_lds_dwordx4 v[182:183], off
	v_lshl_add_u64 v[182:183], s[26:27], 0, v[166:167]
	s_add_i32 m0, s45, 0xe000
	s_nop 0
	global_load_lds_dwordx4 v[182:183], off
	ds_read_b128 v[196:199], v188
	ds_read_b128 v[204:207], v188 offset:1024
	ds_read_b128 v[208:211], v188 offset:2048
	ds_read_b128 v[212:215], v188 offset:3072
	s_waitcnt lgkmcnt(0)
	s_waitcnt vmcnt(8)
	s_barrier
	s_setprio 1
	v_mfma_f32_16x16x32_bf16 v[124:127], v[128:131], v[144:147], 0
	v_mfma_f32_16x16x32_bf16 v[120:123], v[136:139], v[144:147], 0
	v_mfma_f32_16x16x32_bf16 v[108:111], v[128:131], v[152:155], 0
	v_mfma_f32_16x16x32_bf16 v[104:107], v[136:139], v[152:155], 0
	v_mfma_f32_16x16x32_bf16 v[92:95], v[128:131], v[170:173], 0
	v_mfma_f32_16x16x32_bf16 v[88:91], v[136:139], v[170:173], 0
	v_mfma_f32_16x16x32_bf16 v[76:79], v[128:131], v[178:181], 0
	v_mfma_f32_16x16x32_bf16 v[72:75], v[136:139], v[178:181], 0
	v_mfma_f32_16x16x32_bf16 v[124:127], v[132:135], v[148:151], v[124:127]
	v_mfma_f32_16x16x32_bf16 v[120:123], v[140:143], v[148:151], v[120:123]
	v_mfma_f32_16x16x32_bf16 v[108:111], v[132:135], v[156:159], v[108:111]
	v_mfma_f32_16x16x32_bf16 v[104:107], v[140:143], v[156:159], v[104:107]
	v_mfma_f32_16x16x32_bf16 v[92:95], v[132:135], v[174:177], v[92:95]
	v_mfma_f32_16x16x32_bf16 v[88:91], v[140:143], v[174:177], v[88:91]
	v_mfma_f32_16x16x32_bf16 v[76:79], v[132:135], v[192:195], v[76:79]
	v_mfma_f32_16x16x32_bf16 v[72:75], v[140:143], v[192:195], v[72:75]
	v_mfma_f32_16x16x32_bf16 v[116:119], v[196:199], v[144:147], 0
	v_mfma_f32_16x16x32_bf16 v[112:115], v[208:211], v[144:147], 0
	v_mfma_f32_16x16x32_bf16 v[100:103], v[196:199], v[152:155], 0
	v_mfma_f32_16x16x32_bf16 v[96:99], v[208:211], v[152:155], 0
	v_mfma_f32_16x16x32_bf16 v[84:87], v[196:199], v[170:173], 0
	v_mfma_f32_16x16x32_bf16 v[80:83], v[208:211], v[170:173], 0
	v_mfma_f32_16x16x32_bf16 v[68:71], v[196:199], v[178:181], 0
	v_mfma_f32_16x16x32_bf16 v[64:67], v[208:211], v[178:181], 0
	v_mfma_f32_16x16x32_bf16 v[116:119], v[204:207], v[148:151], v[116:119]
	v_mfma_f32_16x16x32_bf16 v[112:115], v[212:215], v[148:151], v[112:115]
	v_mfma_f32_16x16x32_bf16 v[100:103], v[204:207], v[156:159], v[100:103]
	v_mfma_f32_16x16x32_bf16 v[96:99], v[212:215], v[156:159], v[96:99]
	v_mfma_f32_16x16x32_bf16 v[84:87], v[204:207], v[174:177], v[84:87]
	v_mfma_f32_16x16x32_bf16 v[80:83], v[212:215], v[174:177], v[80:83]
	v_mfma_f32_16x16x32_bf16 v[68:71], v[204:207], v[192:195], v[68:71]
	v_mfma_f32_16x16x32_bf16 v[64:67], v[212:215], v[192:195], v[64:67]
	s_setprio 0
	s_barrier
	ds_read_b128 v[144:147], v187 offset:16384
	ds_read_b128 v[148:151], v187 offset:17408
	ds_read_b128 v[152:155], v187 offset:18432
	ds_read_b128 v[156:159], v187 offset:19456
	ds_read_b128 v[170:173], v187 offset:20480
	ds_read_b128 v[174:177], v187 offset:21504
	ds_read_b128 v[178:181], v187 offset:22528
	ds_read_b128 v[192:195], v187 offset:23552
	s_mov_b32 m0, s43
	v_lshl_add_u64 v[182:183], s[28:29], 0, v[160:161]
	global_load_lds_dwordx4 v[182:183], off
	v_lshl_add_u64 v[200:201], s[28:29], 0, v[162:163]
	s_mov_b32 m0, s44
	s_nop 0
	global_load_lds_dwordx4 v[200:201], off
	s_mov_b32 m0, s45
	v_lshl_add_u64 v[216:217], s[30:31], 0, v[160:161]
	global_load_lds_dwordx4 v[216:217], off
	v_lshl_add_u64 v[218:219], s[30:31], 0, v[162:163]
	s_mov_b32 m0, s46
	s_nop 0
	global_load_lds_dwordx4 v[218:219], off
	s_add_u32 s66, s28, 0x40000
	s_addc_u32 s67, s29, 0
	s_mov_b32 m0, s47
	v_lshl_add_u64 v[248:249], s[66:67], 0, v[160:161]
	global_load_lds_dwordx4 v[248:249], off
	v_lshl_add_u64 v[248:249], s[66:67], 0, v[162:163]
	s_mov_b32 m0, s48
	s_nop 0
	global_load_lds_dwordx4 v[248:249], off
	s_waitcnt lgkmcnt(0)
	s_waitcnt vmcnt(8)
	s_barrier
	s_setprio 1
	v_mfma_f32_16x16x32_bf16 v[60:63], v[128:131], v[144:147], 0
	v_mfma_f32_16x16x32_bf16 v[56:59], v[136:139], v[144:147], 0
	v_mfma_f32_16x16x32_bf16 v[44:47], v[128:131], v[152:155], 0
	v_mfma_f32_16x16x32_bf16 v[40:43], v[136:139], v[152:155], 0
	v_mfma_f32_16x16x32_bf16 v[28:31], v[128:131], v[170:173], 0
	v_mfma_f32_16x16x32_bf16 v[24:27], v[136:139], v[170:173], 0
	v_mfma_f32_16x16x32_bf16 v[12:15], v[128:131], v[178:181], 0
	v_mfma_f32_16x16x32_bf16 v[8:11], v[136:139], v[178:181], 0
	v_mfma_f32_16x16x32_bf16 v[60:63], v[132:135], v[148:151], v[60:63]
	v_mfma_f32_16x16x32_bf16 v[56:59], v[140:143], v[148:151], v[56:59]
	v_mfma_f32_16x16x32_bf16 v[44:47], v[132:135], v[156:159], v[44:47]
	v_mfma_f32_16x16x32_bf16 v[40:43], v[140:143], v[156:159], v[40:43]
	v_mfma_f32_16x16x32_bf16 v[28:31], v[132:135], v[174:177], v[28:31]
	v_mfma_f32_16x16x32_bf16 v[24:27], v[140:143], v[174:177], v[24:27]
	v_mfma_f32_16x16x32_bf16 v[12:15], v[132:135], v[192:195], v[12:15]
	v_mfma_f32_16x16x32_bf16 v[8:11], v[140:143], v[192:195], v[8:11]
	v_mfma_f32_16x16x32_bf16 v[52:55], v[196:199], v[144:147], 0
	v_mfma_f32_16x16x32_bf16 v[48:51], v[208:211], v[144:147], 0
	v_mfma_f32_16x16x32_bf16 v[36:39], v[196:199], v[152:155], 0
	v_mfma_f32_16x16x32_bf16 v[32:35], v[208:211], v[152:155], 0
	v_mfma_f32_16x16x32_bf16 v[20:23], v[196:199], v[170:173], 0
	v_mfma_f32_16x16x32_bf16 v[16:19], v[208:211], v[170:173], 0
	v_mfma_f32_16x16x32_bf16 v[4:7], v[196:199], v[178:181], 0
	v_mfma_f32_16x16x32_bf16 v[0:3], v[208:211], v[178:181], 0
	v_mfma_f32_16x16x32_bf16 v[52:55], v[204:207], v[148:151], v[52:55]
	v_mfma_f32_16x16x32_bf16 v[48:51], v[212:215], v[148:151], v[48:51]
	v_mfma_f32_16x16x32_bf16 v[36:39], v[204:207], v[156:159], v[36:39]
	v_mfma_f32_16x16x32_bf16 v[32:35], v[212:215], v[156:159], v[32:35]
	v_mfma_f32_16x16x32_bf16 v[20:23], v[204:207], v[174:177], v[20:23]
	v_mfma_f32_16x16x32_bf16 v[16:19], v[212:215], v[174:177], v[16:19]
	v_mfma_f32_16x16x32_bf16 v[4:7], v[204:207], v[192:195], v[4:7]
	v_mfma_f32_16x16x32_bf16 v[0:3], v[212:215], v[192:195], v[0:3]
	s_setprio 0
	s_barrier
	ds_read_b128 v[128:131], v189
	ds_read_b128 v[132:135], v189 offset:1024
	ds_read_b128 v[136:139], v189 offset:2048
	ds_read_b128 v[140:143], v189 offset:3072
	s_add_u32 s30, s30, 0x40000
	s_addc_u32 s31, s31, 0
	s_mov_b32 m0, s49
	v_lshl_add_u64 v[196:197], s[30:31], 0, v[160:161]
	ds_read_b128 v[144:147], v187 offset:32768
	ds_read_b128 v[148:151], v187 offset:33792
	ds_read_b128 v[152:155], v187 offset:34816
	ds_read_b128 v[156:159], v187 offset:35840
	ds_read_b128 v[170:173], v187 offset:36864
	ds_read_b128 v[174:177], v187 offset:37888
	ds_read_b128 v[178:181], v187 offset:38912
	ds_read_b128 v[192:195], v187 offset:39936
	global_load_lds_dwordx4 v[196:197], off
	v_lshl_add_u64 v[196:197], s[30:31], 0, v[162:163]
	s_mov_b32 m0, s50
	s_nop 0
	global_load_lds_dwordx4 v[196:197], off
	ds_read_b128 v[196:199], v190
	ds_read_b128 v[204:207], v190 offset:1024
	ds_read_b128 v[208:211], v190 offset:2048
	ds_read_b128 v[212:215], v190 offset:3072
	s_waitcnt lgkmcnt(0)
	s_waitcnt vmcnt(8)
	s_barrier
	s_setprio 1
	v_mfma_f32_16x16x32_bf16 v[124:127], v[128:131], v[144:147], v[124:127]
	v_mfma_f32_16x16x32_bf16 v[120:123], v[136:139], v[144:147], v[120:123]
	v_mfma_f32_16x16x32_bf16 v[108:111], v[128:131], v[152:155], v[108:111]
	v_mfma_f32_16x16x32_bf16 v[104:107], v[136:139], v[152:155], v[104:107]
	v_mfma_f32_16x16x32_bf16 v[92:95], v[128:131], v[170:173], v[92:95]
	v_mfma_f32_16x16x32_bf16 v[88:91], v[136:139], v[170:173], v[88:91]
	v_mfma_f32_16x16x32_bf16 v[76:79], v[128:131], v[178:181], v[76:79]
	v_mfma_f32_16x16x32_bf16 v[72:75], v[136:139], v[178:181], v[72:75]
	v_mfma_f32_16x16x32_bf16 v[124:127], v[132:135], v[148:151], v[124:127]
	v_mfma_f32_16x16x32_bf16 v[120:123], v[140:143], v[148:151], v[120:123]
	v_mfma_f32_16x16x32_bf16 v[108:111], v[132:135], v[156:159], v[108:111]
	v_mfma_f32_16x16x32_bf16 v[104:107], v[140:143], v[156:159], v[104:107]
	v_mfma_f32_16x16x32_bf16 v[92:95], v[132:135], v[174:177], v[92:95]
	v_mfma_f32_16x16x32_bf16 v[88:91], v[140:143], v[174:177], v[88:91]
	v_mfma_f32_16x16x32_bf16 v[76:79], v[132:135], v[192:195], v[76:79]
	v_mfma_f32_16x16x32_bf16 v[72:75], v[140:143], v[192:195], v[72:75]
	v_mfma_f32_16x16x32_bf16 v[116:119], v[196:199], v[144:147], v[116:119]
	v_mfma_f32_16x16x32_bf16 v[112:115], v[208:211], v[144:147], v[112:115]
	v_mfma_f32_16x16x32_bf16 v[100:103], v[196:199], v[152:155], v[100:103]
	v_mfma_f32_16x16x32_bf16 v[96:99], v[208:211], v[152:155], v[96:99]
	v_mfma_f32_16x16x32_bf16 v[84:87], v[196:199], v[170:173], v[84:87]
	v_mfma_f32_16x16x32_bf16 v[80:83], v[208:211], v[170:173], v[80:83]
	v_mfma_f32_16x16x32_bf16 v[68:71], v[196:199], v[178:181], v[68:71]
	v_mfma_f32_16x16x32_bf16 v[64:67], v[208:211], v[178:181], v[64:67]
	v_mfma_f32_16x16x32_bf16 v[116:119], v[204:207], v[148:151], v[116:119]
	v_mfma_f32_16x16x32_bf16 v[112:115], v[212:215], v[148:151], v[112:115]
	v_mfma_f32_16x16x32_bf16 v[100:103], v[204:207], v[156:159], v[100:103]
	v_mfma_f32_16x16x32_bf16 v[96:99], v[212:215], v[156:159], v[96:99]
	v_mfma_f32_16x16x32_bf16 v[84:87], v[204:207], v[174:177], v[84:87]
	v_mfma_f32_16x16x32_bf16 v[80:83], v[212:215], v[174:177], v[80:83]
	v_mfma_f32_16x16x32_bf16 v[68:71], v[204:207], v[192:195], v[68:71]
	v_mfma_f32_16x16x32_bf16 v[64:67], v[212:215], v[192:195], v[64:67]
	s_setprio 0
	s_barrier
	ds_read_b128 v[144:147], v187 offset:49152
	ds_read_b128 v[148:151], v187 offset:50176
	ds_read_b128 v[152:155], v187 offset:51200
	ds_read_b128 v[156:159], v187 offset:52224
	ds_read_b128 v[170:173], v187 offset:53248
	ds_read_b128 v[174:177], v187 offset:54272
	ds_read_b128 v[178:181], v187 offset:55296
	ds_read_b128 v[192:195], v187 offset:56320
	s_mov_b32 m0, s54
	v_lshl_add_u64 v[182:183], v[182:183], 0, s[12:13]
	global_load_lds_dwordx4 v[182:183], off
	v_lshl_add_u64 v[182:183], v[200:201], 0, s[12:13]
	s_mov_b32 m0, s55
	s_nop 0
	global_load_lds_dwordx4 v[182:183], off
	s_mov_b32 m0, s56
	v_lshl_add_u64 v[182:183], v[216:217], 0, s[12:13]
	global_load_lds_dwordx4 v[182:183], off
	v_lshl_add_u64 v[182:183], v[218:219], 0, s[12:13]
	s_mov_b32 m0, s57
	s_nop 0
	global_load_lds_dwordx4 v[182:183], off
	s_add_u32 s28, s28, 0x40080
	s_addc_u32 s29, s29, 0
	s_mov_b32 m0, s58
	v_lshl_add_u64 v[248:249], s[28:29], 0, v[160:161]
	global_load_lds_dwordx4 v[248:249], off
	v_lshl_add_u64 v[248:249], s[28:29], 0, v[162:163]
	s_mov_b32 m0, s59
	s_nop 0
	global_load_lds_dwordx4 v[248:249], off
	s_waitcnt lgkmcnt(0)
	s_waitcnt vmcnt(8)
	s_barrier
	s_setprio 1
	v_mfma_f32_16x16x32_bf16 v[60:63], v[128:131], v[144:147], v[60:63]
	v_mfma_f32_16x16x32_bf16 v[56:59], v[136:139], v[144:147], v[56:59]
	v_mfma_f32_16x16x32_bf16 v[44:47], v[128:131], v[152:155], v[44:47]
	v_mfma_f32_16x16x32_bf16 v[40:43], v[136:139], v[152:155], v[40:43]
	v_mfma_f32_16x16x32_bf16 v[28:31], v[128:131], v[170:173], v[28:31]
	v_mfma_f32_16x16x32_bf16 v[24:27], v[136:139], v[170:173], v[24:27]
	v_mfma_f32_16x16x32_bf16 v[12:15], v[128:131], v[178:181], v[12:15]
	v_mfma_f32_16x16x32_bf16 v[8:11], v[136:139], v[178:181], v[8:11]
	v_mfma_f32_16x16x32_bf16 v[60:63], v[132:135], v[148:151], v[60:63]
	v_mfma_f32_16x16x32_bf16 v[56:59], v[140:143], v[148:151], v[56:59]
	v_mfma_f32_16x16x32_bf16 v[44:47], v[132:135], v[156:159], v[44:47]
	v_mfma_f32_16x16x32_bf16 v[40:43], v[140:143], v[156:159], v[40:43]
	v_mfma_f32_16x16x32_bf16 v[28:31], v[132:135], v[174:177], v[28:31]
	v_mfma_f32_16x16x32_bf16 v[24:27], v[140:143], v[174:177], v[24:27]
	v_mfma_f32_16x16x32_bf16 v[12:15], v[132:135], v[192:195], v[12:15]
	v_mfma_f32_16x16x32_bf16 v[8:11], v[140:143], v[192:195], v[8:11]
	v_mfma_f32_16x16x32_bf16 v[52:55], v[196:199], v[144:147], v[52:55]
	v_mfma_f32_16x16x32_bf16 v[48:51], v[208:211], v[144:147], v[48:51]
	v_mfma_f32_16x16x32_bf16 v[36:39], v[196:199], v[152:155], v[36:39]
	v_mfma_f32_16x16x32_bf16 v[32:35], v[208:211], v[152:155], v[32:35]
	v_mfma_f32_16x16x32_bf16 v[20:23], v[196:199], v[170:173], v[20:23]
	v_mfma_f32_16x16x32_bf16 v[16:19], v[208:211], v[170:173], v[16:19]
	v_mfma_f32_16x16x32_bf16 v[4:7], v[196:199], v[178:181], v[4:7]
	v_mfma_f32_16x16x32_bf16 v[0:3], v[208:211], v[178:181], v[0:3]
	v_mfma_f32_16x16x32_bf16 v[52:55], v[204:207], v[148:151], v[52:55]
	v_mfma_f32_16x16x32_bf16 v[48:51], v[212:215], v[148:151], v[48:51]
	v_mfma_f32_16x16x32_bf16 v[36:39], v[204:207], v[156:159], v[36:39]
	v_mfma_f32_16x16x32_bf16 v[32:35], v[212:215], v[156:159], v[32:35]
	v_mfma_f32_16x16x32_bf16 v[20:23], v[204:207], v[174:177], v[20:23]
	v_mfma_f32_16x16x32_bf16 v[16:19], v[212:215], v[174:177], v[16:19]
	v_mfma_f32_16x16x32_bf16 v[4:7], v[204:207], v[192:195], v[4:7]
	v_mfma_f32_16x16x32_bf16 v[0:3], v[212:215], v[192:195], v[0:3]
	s_setprio 0
	s_add_i32 s40, s40, 2
	s_add_u32 s26, s26, 0x100
	s_addc_u32 s27, s27, 0
	s_add_u32 s38, s38, 0x100
	s_addc_u32 s39, s39, 0
	s_cmp_gt_u32 s40, 13
	s_barrier

.LBB0_971:
	s_xor_b64 s[18:19], s[36:37], -1
	s_and_b64 s[30:31], s[36:37], exec
	s_cselect_b32 s25, s15, s27
	s_cselect_b32 s34, s14, s26
	s_cselect_b32 s36, s17, s29
	s_cselect_b32 s37, s16, s28
	s_add_u32 s26, s26, 0x40080
	s_addc_u32 s27, s27, 0
	s_add_u32 s38, s28, 0x100
	s_addc_u32 s39, s29, 0
	s_mov_b32 s40, -2
	s_waitcnt lgkmcnt(0)
	s_waitcnt vmcnt(0)
	ds_read_b128 v[140:143], v146
	ds_read_b128 v[154:157], v146 offset:1024
	ds_read_b128 v[158:161], v146 offset:2048
	ds_read_b128 v[162:165], v146 offset:3072
	s_add_u32 s28, s26, 0xfffc0080
	s_addc_u32 s29, s27, -1
	s_cmp_eq_u32 s40, 12
	s_cselect_b32 s31, s25, s29
	s_cselect_b32 s30, s34, s28
	s_cselect_b32 s29, s36, s39
	s_cselect_b32 s28, s37, s38
	v_lshl_add_u64 v[198:199], s[26:27], 0, v[134:135]
	s_add_i32 m0, s45, 0xc000
	ds_read_b128 v[166:169], v147
	ds_read_b128 v[170:173], v147 offset:1024
	ds_read_b128 v[174:177], v147 offset:2048
	ds_read_b128 v[178:181], v147 offset:3072
	ds_read_b128 v[182:185], v147 offset:4096
	ds_read_b128 v[186:189], v147 offset:5120
	ds_read_b128 v[190:193], v147 offset:6144
	ds_read_b128 v[194:197], v147 offset:7168
	global_load_lds_dwordx4 v[198:199], off
	v_lshl_add_u64 v[198:199], s[26:27], 0, v[136:137]
	s_add_i32 m0, s45, 0xe000
	s_nop 0
	global_load_lds_dwordx4 v[198:199], off
	ds_read_b128 v[198:201], v148
	ds_read_b128 v[204:207], v148 offset:1024
	ds_read_b128 v[208:211], v148 offset:2048
	ds_read_b128 v[212:215], v148 offset:3072
	s_waitcnt lgkmcnt(0)
	s_waitcnt vmcnt(8)
	s_barrier
	s_setprio 1
	v_mfma_f32_16x16x32_bf16 v[124:127], v[140:143], v[166:169], 0
	v_mfma_f32_16x16x32_bf16 v[120:123], v[158:161], v[166:169], 0
	v_mfma_f32_16x16x32_bf16 v[108:111], v[140:143], v[174:177], 0
	v_mfma_f32_16x16x32_bf16 v[104:107], v[158:161], v[174:177], 0
	v_mfma_f32_16x16x32_bf16 v[92:95], v[140:143], v[182:185], 0
	v_mfma_f32_16x16x32_bf16 v[88:91], v[158:161], v[182:185], 0
	v_mfma_f32_16x16x32_bf16 v[76:79], v[140:143], v[190:193], 0
	v_mfma_f32_16x16x32_bf16 v[72:75], v[158:161], v[190:193], 0
	v_mfma_f32_16x16x32_bf16 v[124:127], v[154:157], v[170:173], v[124:127]
	v_mfma_f32_16x16x32_bf16 v[120:123], v[162:165], v[170:173], v[120:123]
	v_mfma_f32_16x16x32_bf16 v[108:111], v[154:157], v[178:181], v[108:111]
	v_mfma_f32_16x16x32_bf16 v[104:107], v[162:165], v[178:181], v[104:107]
	v_mfma_f32_16x16x32_bf16 v[92:95], v[154:157], v[186:189], v[92:95]
	v_mfma_f32_16x16x32_bf16 v[88:91], v[162:165], v[186:189], v[88:91]
	v_mfma_f32_16x16x32_bf16 v[76:79], v[154:157], v[194:197], v[76:79]
	v_mfma_f32_16x16x32_bf16 v[72:75], v[162:165], v[194:197], v[72:75]
	v_mfma_f32_16x16x32_bf16 v[116:119], v[198:201], v[166:169], 0
	v_mfma_f32_16x16x32_bf16 v[112:115], v[208:211], v[166:169], 0
	v_mfma_f32_16x16x32_bf16 v[100:103], v[198:201], v[174:177], 0
	v_mfma_f32_16x16x32_bf16 v[96:99], v[208:211], v[174:177], 0
	v_mfma_f32_16x16x32_bf16 v[84:87], v[198:201], v[182:185], 0
	v_mfma_f32_16x16x32_bf16 v[80:83], v[208:211], v[182:185], 0
	v_mfma_f32_16x16x32_bf16 v[68:71], v[198:201], v[190:193], 0
	v_mfma_f32_16x16x32_bf16 v[64:67], v[208:211], v[190:193], 0
	v_mfma_f32_16x16x32_bf16 v[116:119], v[204:207], v[170:173], v[116:119]
	v_mfma_f32_16x16x32_bf16 v[112:115], v[212:215], v[170:173], v[112:115]
	v_mfma_f32_16x16x32_bf16 v[100:103], v[204:207], v[178:181], v[100:103]
	v_mfma_f32_16x16x32_bf16 v[96:99], v[212:215], v[178:181], v[96:99]
	v_mfma_f32_16x16x32_bf16 v[84:87], v[204:207], v[186:189], v[84:87]
	v_mfma_f32_16x16x32_bf16 v[80:83], v[212:215], v[186:189], v[80:83]
	v_mfma_f32_16x16x32_bf16 v[68:71], v[204:207], v[194:197], v[68:71]
	v_mfma_f32_16x16x32_bf16 v[64:67], v[212:215], v[194:197], v[64:67]
	s_setprio 0
	s_barrier
	ds_read_b128 v[166:169], v147 offset:16384
	ds_read_b128 v[170:173], v147 offset:17408
	ds_read_b128 v[174:177], v147 offset:18432
	ds_read_b128 v[178:181], v147 offset:19456
	ds_read_b128 v[182:185], v147 offset:20480
	ds_read_b128 v[186:189], v147 offset:21504
	ds_read_b128 v[190:193], v147 offset:22528
	ds_read_b128 v[194:197], v147 offset:23552
	s_mov_b32 m0, s43
	v_lshl_add_u64 v[216:217], s[28:29], 0, v[128:129]
	global_load_lds_dwordx4 v[216:217], off
	v_lshl_add_u64 v[218:219], s[28:29], 0, v[130:131]
	s_mov_b32 m0, s44
	s_nop 0
	global_load_lds_dwordx4 v[218:219], off
	s_mov_b32 m0, s45
	v_lshl_add_u64 v[220:221], s[30:31], 0, v[128:129]
	global_load_lds_dwordx4 v[220:221], off
	v_lshl_add_u64 v[222:223], s[30:31], 0, v[130:131]
	s_mov_b32 m0, s46
	s_nop 0
	global_load_lds_dwordx4 v[222:223], off
	s_add_u32 s70, s28, 0x40000
	s_addc_u32 s71, s29, 0
	s_mov_b32 m0, s47
	v_lshl_add_u64 v[248:249], s[70:71], 0, v[128:129]
	global_load_lds_dwordx4 v[248:249], off
	v_lshl_add_u64 v[248:249], s[70:71], 0, v[130:131]
	s_mov_b32 m0, s48
	s_nop 0
	global_load_lds_dwordx4 v[248:249], off
	s_waitcnt lgkmcnt(0)
	s_waitcnt vmcnt(8)
	s_barrier
	s_setprio 1
	v_mfma_f32_16x16x32_bf16 v[60:63], v[140:143], v[166:169], 0
	v_mfma_f32_16x16x32_bf16 v[56:59], v[158:161], v[166:169], 0
	v_mfma_f32_16x16x32_bf16 v[44:47], v[140:143], v[174:177], 0
	v_mfma_f32_16x16x32_bf16 v[40:43], v[158:161], v[174:177], 0
	v_mfma_f32_16x16x32_bf16 v[28:31], v[140:143], v[182:185], 0
	v_mfma_f32_16x16x32_bf16 v[24:27], v[158:161], v[182:185], 0
	v_mfma_f32_16x16x32_bf16 v[12:15], v[140:143], v[190:193], 0
	v_mfma_f32_16x16x32_bf16 v[8:11], v[158:161], v[190:193], 0
	v_mfma_f32_16x16x32_bf16 v[60:63], v[154:157], v[170:173], v[60:63]
	v_mfma_f32_16x16x32_bf16 v[56:59], v[162:165], v[170:173], v[56:59]
	v_mfma_f32_16x16x32_bf16 v[44:47], v[154:157], v[178:181], v[44:47]
	v_mfma_f32_16x16x32_bf16 v[40:43], v[162:165], v[178:181], v[40:43]
	v_mfma_f32_16x16x32_bf16 v[28:31], v[154:157], v[186:189], v[28:31]
	v_mfma_f32_16x16x32_bf16 v[24:27], v[162:165], v[186:189], v[24:27]
	v_mfma_f32_16x16x32_bf16 v[12:15], v[154:157], v[194:197], v[12:15]
	v_mfma_f32_16x16x32_bf16 v[8:11], v[162:165], v[194:197], v[8:11]
	v_mfma_f32_16x16x32_bf16 v[52:55], v[198:201], v[166:169], 0
	v_mfma_f32_16x16x32_bf16 v[48:51], v[208:211], v[166:169], 0
	v_mfma_f32_16x16x32_bf16 v[36:39], v[198:201], v[174:177], 0
	v_mfma_f32_16x16x32_bf16 v[32:35], v[208:211], v[174:177], 0
	v_mfma_f32_16x16x32_bf16 v[20:23], v[198:201], v[182:185], 0
	v_mfma_f32_16x16x32_bf16 v[16:19], v[208:211], v[182:185], 0
	v_mfma_f32_16x16x32_bf16 v[4:7], v[198:201], v[190:193], 0
	v_mfma_f32_16x16x32_bf16 v[0:3], v[208:211], v[190:193], 0
	v_mfma_f32_16x16x32_bf16 v[52:55], v[204:207], v[170:173], v[52:55]
	v_mfma_f32_16x16x32_bf16 v[48:51], v[212:215], v[170:173], v[48:51]
	v_mfma_f32_16x16x32_bf16 v[36:39], v[204:207], v[178:181], v[36:39]
	v_mfma_f32_16x16x32_bf16 v[32:35], v[212:215], v[178:181], v[32:35]
	v_mfma_f32_16x16x32_bf16 v[20:23], v[204:207], v[186:189], v[20:23]
	v_mfma_f32_16x16x32_bf16 v[16:19], v[212:215], v[186:189], v[16:19]
	v_mfma_f32_16x16x32_bf16 v[4:7], v[204:207], v[194:197], v[4:7]
	v_mfma_f32_16x16x32_bf16 v[0:3], v[212:215], v[194:197], v[0:3]
	s_setprio 0
	s_barrier
	ds_read_b128 v[140:143], v149
	ds_read_b128 v[154:157], v149 offset:1024
	ds_read_b128 v[158:161], v149 offset:2048
	ds_read_b128 v[162:165], v149 offset:3072
	s_add_u32 s30, s30, 0x40000
	s_addc_u32 s31, s31, 0
	s_mov_b32 m0, s49
	v_lshl_add_u64 v[198:199], s[30:31], 0, v[128:129]
	ds_read_b128 v[166:169], v147 offset:32768
	ds_read_b128 v[170:173], v147 offset:33792
	ds_read_b128 v[174:177], v147 offset:34816
	ds_read_b128 v[178:181], v147 offset:35840
	ds_read_b128 v[182:185], v147 offset:36864
	ds_read_b128 v[186:189], v147 offset:37888
	ds_read_b128 v[190:193], v147 offset:38912
	ds_read_b128 v[194:197], v147 offset:39936
	global_load_lds_dwordx4 v[198:199], off
	v_lshl_add_u64 v[198:199], s[30:31], 0, v[130:131]
	s_mov_b32 m0, s50
	s_nop 0
	global_load_lds_dwordx4 v[198:199], off
	ds_read_b128 v[198:201], v150
	ds_read_b128 v[204:207], v150 offset:1024
	ds_read_b128 v[208:211], v150 offset:2048
	ds_read_b128 v[212:215], v150 offset:3072
	s_waitcnt lgkmcnt(0)
	s_waitcnt vmcnt(8)
	s_barrier
	s_setprio 1
	v_mfma_f32_16x16x32_bf16 v[124:127], v[140:143], v[166:169], v[124:127]
	v_mfma_f32_16x16x32_bf16 v[120:123], v[158:161], v[166:169], v[120:123]
	v_mfma_f32_16x16x32_bf16 v[108:111], v[140:143], v[174:177], v[108:111]
	v_mfma_f32_16x16x32_bf16 v[104:107], v[158:161], v[174:177], v[104:107]
	v_mfma_f32_16x16x32_bf16 v[92:95], v[140:143], v[182:185], v[92:95]
	v_mfma_f32_16x16x32_bf16 v[88:91], v[158:161], v[182:185], v[88:91]
	v_mfma_f32_16x16x32_bf16 v[76:79], v[140:143], v[190:193], v[76:79]
	v_mfma_f32_16x16x32_bf16 v[72:75], v[158:161], v[190:193], v[72:75]
	v_mfma_f32_16x16x32_bf16 v[124:127], v[154:157], v[170:173], v[124:127]
	v_mfma_f32_16x16x32_bf16 v[120:123], v[162:165], v[170:173], v[120:123]
	v_mfma_f32_16x16x32_bf16 v[108:111], v[154:157], v[178:181], v[108:111]
	v_mfma_f32_16x16x32_bf16 v[104:107], v[162:165], v[178:181], v[104:107]
	v_mfma_f32_16x16x32_bf16 v[92:95], v[154:157], v[186:189], v[92:95]
	v_mfma_f32_16x16x32_bf16 v[88:91], v[162:165], v[186:189], v[88:91]
	v_mfma_f32_16x16x32_bf16 v[76:79], v[154:157], v[194:197], v[76:79]
	v_mfma_f32_16x16x32_bf16 v[72:75], v[162:165], v[194:197], v[72:75]
	v_mfma_f32_16x16x32_bf16 v[116:119], v[198:201], v[166:169], v[116:119]
	v_mfma_f32_16x16x32_bf16 v[112:115], v[208:211], v[166:169], v[112:115]
	v_mfma_f32_16x16x32_bf16 v[100:103], v[198:201], v[174:177], v[100:103]
	v_mfma_f32_16x16x32_bf16 v[96:99], v[208:211], v[174:177], v[96:99]
	v_mfma_f32_16x16x32_bf16 v[84:87], v[198:201], v[182:185], v[84:87]
	v_mfma_f32_16x16x32_bf16 v[80:83], v[208:211], v[182:185], v[80:83]
	v_mfma_f32_16x16x32_bf16 v[68:71], v[198:201], v[190:193], v[68:71]
	v_mfma_f32_16x16x32_bf16 v[64:67], v[208:211], v[190:193], v[64:67]
	v_mfma_f32_16x16x32_bf16 v[116:119], v[204:207], v[170:173], v[116:119]
	v_mfma_f32_16x16x32_bf16 v[112:115], v[212:215], v[170:173], v[112:115]
	v_mfma_f32_16x16x32_bf16 v[100:103], v[204:207], v[178:181], v[100:103]
	v_mfma_f32_16x16x32_bf16 v[96:99], v[212:215], v[178:181], v[96:99]
	v_mfma_f32_16x16x32_bf16 v[84:87], v[204:207], v[186:189], v[84:87]
	v_mfma_f32_16x16x32_bf16 v[80:83], v[212:215], v[186:189], v[80:83]
	v_mfma_f32_16x16x32_bf16 v[68:71], v[204:207], v[194:197], v[68:71]
	v_mfma_f32_16x16x32_bf16 v[64:67], v[212:215], v[194:197], v[64:67]
	s_setprio 0
	s_barrier
	ds_read_b128 v[166:169], v147 offset:49152
	ds_read_b128 v[170:173], v147 offset:50176
	ds_read_b128 v[174:177], v147 offset:51200
	ds_read_b128 v[178:181], v147 offset:52224
	ds_read_b128 v[182:185], v147 offset:53248
	ds_read_b128 v[186:189], v147 offset:54272
	ds_read_b128 v[190:193], v147 offset:55296
	ds_read_b128 v[194:197], v147 offset:56320
	s_mov_b32 m0, s54
	v_lshl_add_u64 v[216:217], v[216:217], 0, s[12:13]
	global_load_lds_dwordx4 v[216:217], off
	v_lshl_add_u64 v[216:217], v[218:219], 0, s[12:13]
	s_mov_b32 m0, s55
	s_nop 0
	global_load_lds_dwordx4 v[216:217], off
	s_mov_b32 m0, s56
	v_lshl_add_u64 v[216:217], v[220:221], 0, s[12:13]
	global_load_lds_dwordx4 v[216:217], off
	v_lshl_add_u64 v[216:217], v[222:223], 0, s[12:13]
	s_mov_b32 m0, s57
	s_nop 0
	global_load_lds_dwordx4 v[216:217], off
	s_add_u32 s28, s28, 0x40080
	s_addc_u32 s29, s29, 0
	s_mov_b32 m0, s58
	v_lshl_add_u64 v[248:249], s[28:29], 0, v[128:129]
	global_load_lds_dwordx4 v[248:249], off
	v_lshl_add_u64 v[248:249], s[28:29], 0, v[130:131]
	s_mov_b32 m0, s59
	s_nop 0
	global_load_lds_dwordx4 v[248:249], off
	s_waitcnt lgkmcnt(0)
	s_waitcnt vmcnt(8)
	s_barrier
	s_setprio 1
	v_mfma_f32_16x16x32_bf16 v[60:63], v[140:143], v[166:169], v[60:63]
	v_mfma_f32_16x16x32_bf16 v[56:59], v[158:161], v[166:169], v[56:59]
	v_mfma_f32_16x16x32_bf16 v[44:47], v[140:143], v[174:177], v[44:47]
	v_mfma_f32_16x16x32_bf16 v[40:43], v[158:161], v[174:177], v[40:43]
	v_mfma_f32_16x16x32_bf16 v[28:31], v[140:143], v[182:185], v[28:31]
	v_mfma_f32_16x16x32_bf16 v[24:27], v[158:161], v[182:185], v[24:27]
	v_mfma_f32_16x16x32_bf16 v[12:15], v[140:143], v[190:193], v[12:15]
	v_mfma_f32_16x16x32_bf16 v[8:11], v[158:161], v[190:193], v[8:11]
	v_mfma_f32_16x16x32_bf16 v[60:63], v[154:157], v[170:173], v[60:63]
	v_mfma_f32_16x16x32_bf16 v[56:59], v[162:165], v[170:173], v[56:59]
	v_mfma_f32_16x16x32_bf16 v[44:47], v[154:157], v[178:181], v[44:47]
	v_mfma_f32_16x16x32_bf16 v[40:43], v[162:165], v[178:181], v[40:43]
	v_mfma_f32_16x16x32_bf16 v[28:31], v[154:157], v[186:189], v[28:31]
	v_mfma_f32_16x16x32_bf16 v[24:27], v[162:165], v[186:189], v[24:27]
	v_mfma_f32_16x16x32_bf16 v[12:15], v[154:157], v[194:197], v[12:15]
	v_mfma_f32_16x16x32_bf16 v[8:11], v[162:165], v[194:197], v[8:11]
	v_mfma_f32_16x16x32_bf16 v[52:55], v[198:201], v[166:169], v[52:55]
	v_mfma_f32_16x16x32_bf16 v[48:51], v[208:211], v[166:169], v[48:51]
	v_mfma_f32_16x16x32_bf16 v[36:39], v[198:201], v[174:177], v[36:39]
	v_mfma_f32_16x16x32_bf16 v[32:35], v[208:211], v[174:177], v[32:35]
	v_mfma_f32_16x16x32_bf16 v[20:23], v[198:201], v[182:185], v[20:23]
	v_mfma_f32_16x16x32_bf16 v[16:19], v[208:211], v[182:185], v[16:19]
	v_mfma_f32_16x16x32_bf16 v[4:7], v[198:201], v[190:193], v[4:7]
	v_mfma_f32_16x16x32_bf16 v[0:3], v[208:211], v[190:193], v[0:3]
	v_mfma_f32_16x16x32_bf16 v[52:55], v[204:207], v[170:173], v[52:55]
	v_mfma_f32_16x16x32_bf16 v[48:51], v[212:215], v[170:173], v[48:51]
	v_mfma_f32_16x16x32_bf16 v[36:39], v[204:207], v[178:181], v[36:39]
	v_mfma_f32_16x16x32_bf16 v[32:35], v[212:215], v[178:181], v[32:35]
	v_mfma_f32_16x16x32_bf16 v[20:23], v[204:207], v[186:189], v[20:23]
	v_mfma_f32_16x16x32_bf16 v[16:19], v[212:215], v[186:189], v[16:19]
	v_mfma_f32_16x16x32_bf16 v[4:7], v[204:207], v[194:197], v[4:7]
	v_mfma_f32_16x16x32_bf16 v[0:3], v[212:215], v[194:197], v[0:3]
	s_setprio 0
	s_add_i32 s40, s40, 2
	s_add_u32 s26, s26, 0x100
	s_addc_u32 s27, s27, 0
	s_add_u32 s38, s38, 0x100
	s_addc_u32 s39, s39, 0
	s_cmp_gt_u32 s40, 13
	s_barrier

.LBB0_1127:
	s_xor_b64 s[16:17], s[34:35], -1
	s_and_b64 s[28:29], s[34:35], exec
	s_cselect_b32 s19, s13, s25
	s_cselect_b32 s30, s12, s24
	s_cselect_b32 s34, s15, s27
	s_cselect_b32 s35, s14, s26
	s_add_u32 s24, s24, 0x20080
	s_addc_u32 s25, s25, 0
	s_add_u32 s36, s26, 0x100
	s_addc_u32 s37, s27, 0
	s_mov_b32 s38, -2
	s_waitcnt lgkmcnt(0)
	ds_read_b128 v[128:131], v186
	ds_read_b128 v[132:135], v186 offset:1024
	ds_read_b128 v[136:139], v186 offset:2048
	ds_read_b128 v[140:143], v186 offset:3072
	s_add_u32 s26, s24, 0xfffe0080
	s_addc_u32 s27, s25, -1
	s_cmp_eq_u32 s38, 4
	s_cselect_b32 s29, s19, s27
	s_cselect_b32 s28, s30, s26
	s_cselect_b32 s27, s34, s37
	s_cselect_b32 s26, s35, s36
	v_lshl_add_u64 v[182:183], s[24:25], 0, v[164:165]
	s_add_i32 m0, s42, 0xc000
	ds_read_b128 v[144:147], v187
	ds_read_b128 v[148:151], v187 offset:1024
	ds_read_b128 v[152:155], v187 offset:2048
	ds_read_b128 v[156:159], v187 offset:3072
	ds_read_b128 v[170:173], v187 offset:4096
	ds_read_b128 v[174:177], v187 offset:5120
	ds_read_b128 v[178:181], v187 offset:6144
	ds_read_b128 v[192:195], v187 offset:7168
	global_load_lds_dwordx4 v[182:183], off
	v_lshl_add_u64 v[182:183], s[24:25], 0, v[166:167]
	s_add_i32 m0, s42, 0xe000
	s_nop 0
	global_load_lds_dwordx4 v[182:183], off
	ds_read_b128 v[196:199], v188
	ds_read_b128 v[204:207], v188 offset:1024
	ds_read_b128 v[208:211], v188 offset:2048
	ds_read_b128 v[212:215], v188 offset:3072
	s_waitcnt lgkmcnt(0)
	s_waitcnt vmcnt(8)
	s_barrier
	s_setprio 1
	v_mfma_f32_16x16x32_bf16 v[124:127], v[128:131], v[144:147], 0
	v_mfma_f32_16x16x32_bf16 v[120:123], v[136:139], v[144:147], 0
	v_mfma_f32_16x16x32_bf16 v[108:111], v[128:131], v[152:155], 0
	v_mfma_f32_16x16x32_bf16 v[104:107], v[136:139], v[152:155], 0
	v_mfma_f32_16x16x32_bf16 v[92:95], v[128:131], v[170:173], 0
	v_mfma_f32_16x16x32_bf16 v[88:91], v[136:139], v[170:173], 0
	v_mfma_f32_16x16x32_bf16 v[76:79], v[128:131], v[178:181], 0
	v_mfma_f32_16x16x32_bf16 v[72:75], v[136:139], v[178:181], 0
	v_mfma_f32_16x16x32_bf16 v[124:127], v[132:135], v[148:151], v[124:127]
	v_mfma_f32_16x16x32_bf16 v[120:123], v[140:143], v[148:151], v[120:123]
	v_mfma_f32_16x16x32_bf16 v[108:111], v[132:135], v[156:159], v[108:111]
	v_mfma_f32_16x16x32_bf16 v[104:107], v[140:143], v[156:159], v[104:107]
	v_mfma_f32_16x16x32_bf16 v[92:95], v[132:135], v[174:177], v[92:95]
	v_mfma_f32_16x16x32_bf16 v[88:91], v[140:143], v[174:177], v[88:91]
	v_mfma_f32_16x16x32_bf16 v[76:79], v[132:135], v[192:195], v[76:79]
	v_mfma_f32_16x16x32_bf16 v[72:75], v[140:143], v[192:195], v[72:75]
	v_mfma_f32_16x16x32_bf16 v[116:119], v[196:199], v[144:147], 0
	v_mfma_f32_16x16x32_bf16 v[112:115], v[208:211], v[144:147], 0
	v_mfma_f32_16x16x32_bf16 v[100:103], v[196:199], v[152:155], 0
	v_mfma_f32_16x16x32_bf16 v[96:99], v[208:211], v[152:155], 0
	v_mfma_f32_16x16x32_bf16 v[84:87], v[196:199], v[170:173], 0
	v_mfma_f32_16x16x32_bf16 v[80:83], v[208:211], v[170:173], 0
	v_mfma_f32_16x16x32_bf16 v[68:71], v[196:199], v[178:181], 0
	v_mfma_f32_16x16x32_bf16 v[64:67], v[208:211], v[178:181], 0
	v_mfma_f32_16x16x32_bf16 v[116:119], v[204:207], v[148:151], v[116:119]
	v_mfma_f32_16x16x32_bf16 v[112:115], v[212:215], v[148:151], v[112:115]
	v_mfma_f32_16x16x32_bf16 v[100:103], v[204:207], v[156:159], v[100:103]
	v_mfma_f32_16x16x32_bf16 v[96:99], v[212:215], v[156:159], v[96:99]
	v_mfma_f32_16x16x32_bf16 v[84:87], v[204:207], v[174:177], v[84:87]
	v_mfma_f32_16x16x32_bf16 v[80:83], v[212:215], v[174:177], v[80:83]
	v_mfma_f32_16x16x32_bf16 v[68:71], v[204:207], v[192:195], v[68:71]
	v_mfma_f32_16x16x32_bf16 v[64:67], v[212:215], v[192:195], v[64:67]
	s_setprio 0
	s_barrier
	ds_read_b128 v[144:147], v187 offset:16384
	ds_read_b128 v[148:151], v187 offset:17408
	ds_read_b128 v[152:155], v187 offset:18432
	ds_read_b128 v[156:159], v187 offset:19456
	ds_read_b128 v[170:173], v187 offset:20480
	ds_read_b128 v[174:177], v187 offset:21504
	ds_read_b128 v[178:181], v187 offset:22528
	ds_read_b128 v[192:195], v187 offset:23552
	s_mov_b32 m0, s40
	v_lshl_add_u64 v[182:183], s[26:27], 0, v[160:161]
	global_load_lds_dwordx4 v[182:183], off
	v_lshl_add_u64 v[200:201], s[26:27], 0, v[162:163]
	s_mov_b32 m0, s41
	s_nop 0
	global_load_lds_dwordx4 v[200:201], off
	s_mov_b32 m0, s42
	v_lshl_add_u64 v[216:217], s[28:29], 0, v[160:161]
	global_load_lds_dwordx4 v[216:217], off
	v_lshl_add_u64 v[218:219], s[28:29], 0, v[162:163]
	s_mov_b32 m0, s43
	s_nop 0
	global_load_lds_dwordx4 v[218:219], off
	s_add_u32 s64, s26, 0x20000
	s_addc_u32 s65, s27, 0
	s_mov_b32 m0, s44
	v_lshl_add_u64 v[248:249], s[64:65], 0, v[160:161]
	global_load_lds_dwordx4 v[248:249], off
	v_lshl_add_u64 v[248:249], s[64:65], 0, v[162:163]
	s_mov_b32 m0, s45
	s_nop 0
	global_load_lds_dwordx4 v[248:249], off
	s_waitcnt lgkmcnt(0)
	s_waitcnt vmcnt(8)
	s_barrier
	s_setprio 1
	v_mfma_f32_16x16x32_bf16 v[60:63], v[128:131], v[144:147], 0
	v_mfma_f32_16x16x32_bf16 v[56:59], v[136:139], v[144:147], 0
	v_mfma_f32_16x16x32_bf16 v[44:47], v[128:131], v[152:155], 0
	v_mfma_f32_16x16x32_bf16 v[40:43], v[136:139], v[152:155], 0
	v_mfma_f32_16x16x32_bf16 v[28:31], v[128:131], v[170:173], 0
	v_mfma_f32_16x16x32_bf16 v[24:27], v[136:139], v[170:173], 0
	v_mfma_f32_16x16x32_bf16 v[12:15], v[128:131], v[178:181], 0
	v_mfma_f32_16x16x32_bf16 v[8:11], v[136:139], v[178:181], 0
	v_mfma_f32_16x16x32_bf16 v[60:63], v[132:135], v[148:151], v[60:63]
	v_mfma_f32_16x16x32_bf16 v[56:59], v[140:143], v[148:151], v[56:59]
	v_mfma_f32_16x16x32_bf16 v[44:47], v[132:135], v[156:159], v[44:47]
	v_mfma_f32_16x16x32_bf16 v[40:43], v[140:143], v[156:159], v[40:43]
	v_mfma_f32_16x16x32_bf16 v[28:31], v[132:135], v[174:177], v[28:31]
	v_mfma_f32_16x16x32_bf16 v[24:27], v[140:143], v[174:177], v[24:27]
	v_mfma_f32_16x16x32_bf16 v[12:15], v[132:135], v[192:195], v[12:15]
	v_mfma_f32_16x16x32_bf16 v[8:11], v[140:143], v[192:195], v[8:11]
	v_mfma_f32_16x16x32_bf16 v[52:55], v[196:199], v[144:147], 0
	v_mfma_f32_16x16x32_bf16 v[48:51], v[208:211], v[144:147], 0
	v_mfma_f32_16x16x32_bf16 v[36:39], v[196:199], v[152:155], 0
	v_mfma_f32_16x16x32_bf16 v[32:35], v[208:211], v[152:155], 0
	v_mfma_f32_16x16x32_bf16 v[20:23], v[196:199], v[170:173], 0
	v_mfma_f32_16x16x32_bf16 v[16:19], v[208:211], v[170:173], 0
	v_mfma_f32_16x16x32_bf16 v[4:7], v[196:199], v[178:181], 0
	v_mfma_f32_16x16x32_bf16 v[0:3], v[208:211], v[178:181], 0
	v_mfma_f32_16x16x32_bf16 v[52:55], v[204:207], v[148:151], v[52:55]
	v_mfma_f32_16x16x32_bf16 v[48:51], v[212:215], v[148:151], v[48:51]
	v_mfma_f32_16x16x32_bf16 v[36:39], v[204:207], v[156:159], v[36:39]
	v_mfma_f32_16x16x32_bf16 v[32:35], v[212:215], v[156:159], v[32:35]
	v_mfma_f32_16x16x32_bf16 v[20:23], v[204:207], v[174:177], v[20:23]
	v_mfma_f32_16x16x32_bf16 v[16:19], v[212:215], v[174:177], v[16:19]
	v_mfma_f32_16x16x32_bf16 v[4:7], v[204:207], v[192:195], v[4:7]
	v_mfma_f32_16x16x32_bf16 v[0:3], v[212:215], v[192:195], v[0:3]
	s_setprio 0
	s_barrier
	ds_read_b128 v[128:131], v189
	ds_read_b128 v[132:135], v189 offset:1024
	ds_read_b128 v[136:139], v189 offset:2048
	ds_read_b128 v[140:143], v189 offset:3072
	s_add_u32 s28, s28, 0x20000
	s_addc_u32 s29, s29, 0
	s_mov_b32 m0, s46
	v_lshl_add_u64 v[196:197], s[28:29], 0, v[160:161]
	ds_read_b128 v[144:147], v187 offset:32768
	ds_read_b128 v[148:151], v187 offset:33792
	ds_read_b128 v[152:155], v187 offset:34816
	ds_read_b128 v[156:159], v187 offset:35840
	ds_read_b128 v[170:173], v187 offset:36864
	ds_read_b128 v[174:177], v187 offset:37888
	ds_read_b128 v[178:181], v187 offset:38912
	ds_read_b128 v[192:195], v187 offset:39936
	global_load_lds_dwordx4 v[196:197], off
	v_lshl_add_u64 v[196:197], s[28:29], 0, v[162:163]
	s_mov_b32 m0, s47
	s_nop 0
	global_load_lds_dwordx4 v[196:197], off
	ds_read_b128 v[196:199], v190
	ds_read_b128 v[204:207], v190 offset:1024
	ds_read_b128 v[208:211], v190 offset:2048
	ds_read_b128 v[212:215], v190 offset:3072
	s_waitcnt lgkmcnt(0)
	s_waitcnt vmcnt(8)
	s_barrier
	s_setprio 1
	v_mfma_f32_16x16x32_bf16 v[124:127], v[128:131], v[144:147], v[124:127]
	v_mfma_f32_16x16x32_bf16 v[120:123], v[136:139], v[144:147], v[120:123]
	v_mfma_f32_16x16x32_bf16 v[108:111], v[128:131], v[152:155], v[108:111]
	v_mfma_f32_16x16x32_bf16 v[104:107], v[136:139], v[152:155], v[104:107]
	v_mfma_f32_16x16x32_bf16 v[92:95], v[128:131], v[170:173], v[92:95]
	v_mfma_f32_16x16x32_bf16 v[88:91], v[136:139], v[170:173], v[88:91]
	v_mfma_f32_16x16x32_bf16 v[76:79], v[128:131], v[178:181], v[76:79]
	v_mfma_f32_16x16x32_bf16 v[72:75], v[136:139], v[178:181], v[72:75]
	v_mfma_f32_16x16x32_bf16 v[124:127], v[132:135], v[148:151], v[124:127]
	v_mfma_f32_16x16x32_bf16 v[120:123], v[140:143], v[148:151], v[120:123]
	v_mfma_f32_16x16x32_bf16 v[108:111], v[132:135], v[156:159], v[108:111]
	v_mfma_f32_16x16x32_bf16 v[104:107], v[140:143], v[156:159], v[104:107]
	v_mfma_f32_16x16x32_bf16 v[92:95], v[132:135], v[174:177], v[92:95]
	v_mfma_f32_16x16x32_bf16 v[88:91], v[140:143], v[174:177], v[88:91]
	v_mfma_f32_16x16x32_bf16 v[76:79], v[132:135], v[192:195], v[76:79]
	v_mfma_f32_16x16x32_bf16 v[72:75], v[140:143], v[192:195], v[72:75]
	v_mfma_f32_16x16x32_bf16 v[116:119], v[196:199], v[144:147], v[116:119]
	v_mfma_f32_16x16x32_bf16 v[112:115], v[208:211], v[144:147], v[112:115]
	v_mfma_f32_16x16x32_bf16 v[100:103], v[196:199], v[152:155], v[100:103]
	v_mfma_f32_16x16x32_bf16 v[96:99], v[208:211], v[152:155], v[96:99]
	v_mfma_f32_16x16x32_bf16 v[84:87], v[196:199], v[170:173], v[84:87]
	v_mfma_f32_16x16x32_bf16 v[80:83], v[208:211], v[170:173], v[80:83]
	v_mfma_f32_16x16x32_bf16 v[68:71], v[196:199], v[178:181], v[68:71]
	v_mfma_f32_16x16x32_bf16 v[64:67], v[208:211], v[178:181], v[64:67]
	v_mfma_f32_16x16x32_bf16 v[116:119], v[204:207], v[148:151], v[116:119]
	v_mfma_f32_16x16x32_bf16 v[112:115], v[212:215], v[148:151], v[112:115]
	v_mfma_f32_16x16x32_bf16 v[100:103], v[204:207], v[156:159], v[100:103]
	v_mfma_f32_16x16x32_bf16 v[96:99], v[212:215], v[156:159], v[96:99]
	v_mfma_f32_16x16x32_bf16 v[84:87], v[204:207], v[174:177], v[84:87]
	v_mfma_f32_16x16x32_bf16 v[80:83], v[212:215], v[174:177], v[80:83]
	v_mfma_f32_16x16x32_bf16 v[68:71], v[204:207], v[192:195], v[68:71]
	v_mfma_f32_16x16x32_bf16 v[64:67], v[212:215], v[192:195], v[64:67]
	s_setprio 0
	s_barrier
	ds_read_b128 v[144:147], v187 offset:49152
	ds_read_b128 v[148:151], v187 offset:50176
	ds_read_b128 v[152:155], v187 offset:51200
	ds_read_b128 v[156:159], v187 offset:52224
	ds_read_b128 v[170:173], v187 offset:53248
	ds_read_b128 v[174:177], v187 offset:54272
	ds_read_b128 v[178:181], v187 offset:55296
	ds_read_b128 v[192:195], v187 offset:56320
	s_mov_b32 m0, s51
	v_lshl_add_u64 v[182:183], v[182:183], 0, s[10:11]
	global_load_lds_dwordx4 v[182:183], off
	v_lshl_add_u64 v[182:183], v[200:201], 0, s[10:11]
	s_mov_b32 m0, s52
	s_nop 0
	global_load_lds_dwordx4 v[182:183], off
	s_mov_b32 m0, s53
	v_lshl_add_u64 v[182:183], v[216:217], 0, s[10:11]
	global_load_lds_dwordx4 v[182:183], off
	v_lshl_add_u64 v[182:183], v[218:219], 0, s[10:11]
	s_mov_b32 m0, s54
	s_nop 0
	global_load_lds_dwordx4 v[182:183], off
	s_add_u32 s26, s26, 0x20080
	s_addc_u32 s27, s27, 0
	s_mov_b32 m0, s55
	v_lshl_add_u64 v[248:249], s[26:27], 0, v[160:161]
	global_load_lds_dwordx4 v[248:249], off
	v_lshl_add_u64 v[248:249], s[26:27], 0, v[162:163]
	s_mov_b32 m0, s56
	s_nop 0
	global_load_lds_dwordx4 v[248:249], off
	s_waitcnt lgkmcnt(0)
	s_waitcnt vmcnt(8)
	s_barrier
	s_setprio 1
	v_mfma_f32_16x16x32_bf16 v[60:63], v[128:131], v[144:147], v[60:63]
	v_mfma_f32_16x16x32_bf16 v[56:59], v[136:139], v[144:147], v[56:59]
	v_mfma_f32_16x16x32_bf16 v[44:47], v[128:131], v[152:155], v[44:47]
	v_mfma_f32_16x16x32_bf16 v[40:43], v[136:139], v[152:155], v[40:43]
	v_mfma_f32_16x16x32_bf16 v[28:31], v[128:131], v[170:173], v[28:31]
	v_mfma_f32_16x16x32_bf16 v[24:27], v[136:139], v[170:173], v[24:27]
	v_mfma_f32_16x16x32_bf16 v[12:15], v[128:131], v[178:181], v[12:15]
	v_mfma_f32_16x16x32_bf16 v[8:11], v[136:139], v[178:181], v[8:11]
	v_mfma_f32_16x16x32_bf16 v[60:63], v[132:135], v[148:151], v[60:63]
	v_mfma_f32_16x16x32_bf16 v[56:59], v[140:143], v[148:151], v[56:59]
	v_mfma_f32_16x16x32_bf16 v[44:47], v[132:135], v[156:159], v[44:47]
	v_mfma_f32_16x16x32_bf16 v[40:43], v[140:143], v[156:159], v[40:43]
	v_mfma_f32_16x16x32_bf16 v[28:31], v[132:135], v[174:177], v[28:31]
	v_mfma_f32_16x16x32_bf16 v[24:27], v[140:143], v[174:177], v[24:27]
	v_mfma_f32_16x16x32_bf16 v[12:15], v[132:135], v[192:195], v[12:15]
	v_mfma_f32_16x16x32_bf16 v[8:11], v[140:143], v[192:195], v[8:11]
	v_mfma_f32_16x16x32_bf16 v[52:55], v[196:199], v[144:147], v[52:55]
	v_mfma_f32_16x16x32_bf16 v[48:51], v[208:211], v[144:147], v[48:51]
	v_mfma_f32_16x16x32_bf16 v[36:39], v[196:199], v[152:155], v[36:39]
	v_mfma_f32_16x16x32_bf16 v[32:35], v[208:211], v[152:155], v[32:35]
	v_mfma_f32_16x16x32_bf16 v[20:23], v[196:199], v[170:173], v[20:23]
	v_mfma_f32_16x16x32_bf16 v[16:19], v[208:211], v[170:173], v[16:19]
	v_mfma_f32_16x16x32_bf16 v[4:7], v[196:199], v[178:181], v[4:7]
	v_mfma_f32_16x16x32_bf16 v[0:3], v[208:211], v[178:181], v[0:3]
	v_mfma_f32_16x16x32_bf16 v[52:55], v[204:207], v[148:151], v[52:55]
	v_mfma_f32_16x16x32_bf16 v[48:51], v[212:215], v[148:151], v[48:51]
	v_mfma_f32_16x16x32_bf16 v[36:39], v[204:207], v[156:159], v[36:39]
	v_mfma_f32_16x16x32_bf16 v[32:35], v[212:215], v[156:159], v[32:35]
	v_mfma_f32_16x16x32_bf16 v[20:23], v[204:207], v[174:177], v[20:23]
	v_mfma_f32_16x16x32_bf16 v[16:19], v[212:215], v[174:177], v[16:19]
	v_mfma_f32_16x16x32_bf16 v[4:7], v[204:207], v[192:195], v[4:7]
	v_mfma_f32_16x16x32_bf16 v[0:3], v[212:215], v[192:195], v[0:3]
	s_setprio 0
	s_add_i32 s38, s38, 2
	s_add_u32 s24, s24, 0x100
	s_addc_u32 s25, s25, 0
	s_add_u32 s36, s36, 0x100
	s_addc_u32 s37, s37, 0
	s_cmp_gt_u32 s38, 5
	s_barrier

.LBB0_1242:
	s_xor_b64 s[26:27], s[36:37], -1
	s_and_b64 s[36:37], s[36:37], exec
	s_cselect_b32 s11, s19, s31
	s_cselect_b32 s17, s18, s30
	s_cselect_b32 s29, s25, s35
	s_cselect_b32 s38, s24, s34
	s_add_u32 s30, s30, 0x40080
	s_addc_u32 s31, s31, 0
	s_add_u32 s39, s34, 0x100
	s_addc_u32 s40, s35, 0
	s_mov_b32 s41, -2
	ds_read_b128 v[170:173], v162
	ds_read_b128 v[174:177], v162 offset:1024
	ds_read_b128 v[178:181], v162 offset:2048
	ds_read_b128 v[182:185], v162 offset:3072
	s_add_u32 s34, s30, 0xfffc0080
	s_addc_u32 s35, s31, -1
	s_cmp_eq_u32 s41, 12
	s_cselect_b32 s37, s11, s35
	s_cselect_b32 s36, s17, s34
	s_cselect_b32 s35, s29, s40
	s_cselect_b32 s34, s38, s39
	v_lshl_add_u64 v[144:145], s[30:31], 0, v[134:135]
	s_add_i32 m0, s48, 0xc000
	ds_read_b128 v[186:189], v163
	ds_read_b128 v[190:193], v163 offset:1024
	ds_read_b128 v[194:197], v163 offset:2048
	ds_read_b128 v[198:201], v163 offset:3072
	ds_read_b128 v[204:207], v163 offset:4096
	ds_read_b128 v[208:211], v163 offset:5120
	ds_read_b128 v[212:215], v163 offset:6144
	ds_read_b128 v[216:219], v163 offset:7168
	global_load_lds_dwordx4 v[144:145], off
	v_lshl_add_u64 v[144:145], s[30:31], 0, v[136:137]
	s_add_i32 m0, s48, 0xe000
	s_nop 0
	global_load_lds_dwordx4 v[144:145], off
	ds_read_b128 v[220:223], v164
	ds_read_b128 v[224:227], v164 offset:1024
	ds_read_b128 v[228:231], v164 offset:2048
	ds_read_b128 v[232:235], v164 offset:3072
	s_waitcnt lgkmcnt(0)
	s_waitcnt vmcnt(8)
	s_barrier
	s_setprio 1
	v_mfma_f32_16x16x32_bf16 v[124:127], v[170:173], v[186:189], 0
	v_mfma_f32_16x16x32_bf16 v[120:123], v[178:181], v[186:189], 0
	v_mfma_f32_16x16x32_bf16 v[112:115], v[170:173], v[194:197], 0
	v_mfma_f32_16x16x32_bf16 v[104:107], v[178:181], v[194:197], 0
	v_mfma_f32_16x16x32_bf16 v[96:99], v[170:173], v[204:207], 0
	v_mfma_f32_16x16x32_bf16 v[88:91], v[178:181], v[204:207], 0
	v_mfma_f32_16x16x32_bf16 v[80:83], v[170:173], v[212:215], 0
	v_mfma_f32_16x16x32_bf16 v[72:75], v[178:181], v[212:215], 0
	v_mfma_f32_16x16x32_bf16 v[124:127], v[174:177], v[190:193], v[124:127]
	v_mfma_f32_16x16x32_bf16 v[120:123], v[182:185], v[190:193], v[120:123]
	v_mfma_f32_16x16x32_bf16 v[112:115], v[174:177], v[198:201], v[112:115]
	v_mfma_f32_16x16x32_bf16 v[104:107], v[182:185], v[198:201], v[104:107]
	v_mfma_f32_16x16x32_bf16 v[96:99], v[174:177], v[208:211], v[96:99]
	v_mfma_f32_16x16x32_bf16 v[88:91], v[182:185], v[208:211], v[88:91]
	v_mfma_f32_16x16x32_bf16 v[80:83], v[174:177], v[216:219], v[80:83]
	v_mfma_f32_16x16x32_bf16 v[72:75], v[182:185], v[216:219], v[72:75]
	v_mfma_f32_16x16x32_bf16 v[116:119], v[220:223], v[186:189], 0
	v_mfma_f32_16x16x32_bf16 v[108:111], v[228:231], v[186:189], 0
	v_mfma_f32_16x16x32_bf16 v[100:103], v[220:223], v[194:197], 0
	v_mfma_f32_16x16x32_bf16 v[92:95], v[228:231], v[194:197], 0
	v_mfma_f32_16x16x32_bf16 v[84:87], v[220:223], v[204:207], 0
	v_mfma_f32_16x16x32_bf16 v[76:79], v[228:231], v[204:207], 0
	v_mfma_f32_16x16x32_bf16 v[68:71], v[220:223], v[212:215], 0
	v_mfma_f32_16x16x32_bf16 v[64:67], v[228:231], v[212:215], 0
	v_mfma_f32_16x16x32_bf16 v[116:119], v[224:227], v[190:193], v[116:119]
	v_mfma_f32_16x16x32_bf16 v[108:111], v[232:235], v[190:193], v[108:111]
	v_mfma_f32_16x16x32_bf16 v[100:103], v[224:227], v[198:201], v[100:103]
	v_mfma_f32_16x16x32_bf16 v[92:95], v[232:235], v[198:201], v[92:95]
	v_mfma_f32_16x16x32_bf16 v[84:87], v[224:227], v[208:211], v[84:87]
	v_mfma_f32_16x16x32_bf16 v[76:79], v[232:235], v[208:211], v[76:79]
	v_mfma_f32_16x16x32_bf16 v[68:71], v[224:227], v[216:219], v[68:71]
	v_mfma_f32_16x16x32_bf16 v[64:67], v[232:235], v[216:219], v[64:67]
	s_setprio 0
	s_barrier
	ds_read_b128 v[186:189], v163 offset:16384
	ds_read_b128 v[190:193], v163 offset:17408
	ds_read_b128 v[194:197], v163 offset:18432
	ds_read_b128 v[198:201], v163 offset:19456
	ds_read_b128 v[204:207], v163 offset:20480
	ds_read_b128 v[208:211], v163 offset:21504
	ds_read_b128 v[212:215], v163 offset:22528
	ds_read_b128 v[216:219], v163 offset:23552
	s_mov_b32 m0, s46
	v_lshl_add_u64 v[144:145], s[34:35], 0, v[128:129]
	global_load_lds_dwordx4 v[144:145], off
	v_lshl_add_u64 v[236:237], s[34:35], 0, v[130:131]
	s_mov_b32 m0, s47
	s_nop 0
	global_load_lds_dwordx4 v[236:237], off
	s_mov_b32 m0, s48
	v_lshl_add_u64 v[238:239], s[36:37], 0, v[128:129]
	global_load_lds_dwordx4 v[238:239], off
	v_lshl_add_u64 v[240:241], s[36:37], 0, v[130:131]
	s_mov_b32 m0, s49
	s_nop 0
	global_load_lds_dwordx4 v[240:241], off
	s_add_u32 s72, s34, 0x40000
	s_addc_u32 s73, s35, 0
	s_mov_b32 m0, s50
	v_lshl_add_u64 v[248:249], s[72:73], 0, v[128:129]
	global_load_lds_dwordx4 v[248:249], off
	v_lshl_add_u64 v[248:249], s[72:73], 0, v[130:131]
	s_mov_b32 m0, s51
	s_nop 0
	global_load_lds_dwordx4 v[248:249], off
	s_waitcnt lgkmcnt(0)
	s_waitcnt vmcnt(8)
	s_barrier
	s_setprio 1
	v_mfma_f32_16x16x32_bf16 v[60:63], v[170:173], v[186:189], 0
	v_mfma_f32_16x16x32_bf16 v[56:59], v[178:181], v[186:189], 0
	v_mfma_f32_16x16x32_bf16 v[48:51], v[170:173], v[194:197], 0
	v_mfma_f32_16x16x32_bf16 v[40:43], v[178:181], v[194:197], 0
	v_mfma_f32_16x16x32_bf16 v[32:35], v[170:173], v[204:207], 0
	v_mfma_f32_16x16x32_bf16 v[24:27], v[178:181], v[204:207], 0
	v_mfma_f32_16x16x32_bf16 v[16:19], v[170:173], v[212:215], 0
	v_mfma_f32_16x16x32_bf16 v[8:11], v[178:181], v[212:215], 0
	v_mfma_f32_16x16x32_bf16 v[60:63], v[174:177], v[190:193], v[60:63]
	v_mfma_f32_16x16x32_bf16 v[56:59], v[182:185], v[190:193], v[56:59]
	v_mfma_f32_16x16x32_bf16 v[48:51], v[174:177], v[198:201], v[48:51]
	v_mfma_f32_16x16x32_bf16 v[40:43], v[182:185], v[198:201], v[40:43]
	v_mfma_f32_16x16x32_bf16 v[32:35], v[174:177], v[208:211], v[32:35]
	v_mfma_f32_16x16x32_bf16 v[24:27], v[182:185], v[208:211], v[24:27]
	v_mfma_f32_16x16x32_bf16 v[16:19], v[174:177], v[216:219], v[16:19]
	v_mfma_f32_16x16x32_bf16 v[8:11], v[182:185], v[216:219], v[8:11]
	v_mfma_f32_16x16x32_bf16 v[52:55], v[220:223], v[186:189], 0
	v_mfma_f32_16x16x32_bf16 v[44:47], v[228:231], v[186:189], 0
	v_mfma_f32_16x16x32_bf16 v[36:39], v[220:223], v[194:197], 0
	v_mfma_f32_16x16x32_bf16 v[28:31], v[228:231], v[194:197], 0
	v_mfma_f32_16x16x32_bf16 v[20:23], v[220:223], v[204:207], 0
	v_mfma_f32_16x16x32_bf16 v[12:15], v[228:231], v[204:207], 0
	v_mfma_f32_16x16x32_bf16 v[4:7], v[220:223], v[212:215], 0
	v_mfma_f32_16x16x32_bf16 v[0:3], v[228:231], v[212:215], 0
	v_mfma_f32_16x16x32_bf16 v[52:55], v[224:227], v[190:193], v[52:55]
	v_mfma_f32_16x16x32_bf16 v[44:47], v[232:235], v[190:193], v[44:47]
	v_mfma_f32_16x16x32_bf16 v[36:39], v[224:227], v[198:201], v[36:39]
	v_mfma_f32_16x16x32_bf16 v[28:31], v[232:235], v[198:201], v[28:31]
	v_mfma_f32_16x16x32_bf16 v[20:23], v[224:227], v[208:211], v[20:23]
	v_mfma_f32_16x16x32_bf16 v[12:15], v[232:235], v[208:211], v[12:15]
	v_mfma_f32_16x16x32_bf16 v[4:7], v[224:227], v[216:219], v[4:7]
	v_mfma_f32_16x16x32_bf16 v[0:3], v[232:235], v[216:219], v[0:3]
	s_setprio 0
	s_barrier
	ds_read_b128 v[170:173], v165
	ds_read_b128 v[174:177], v165 offset:1024
	ds_read_b128 v[178:181], v165 offset:2048
	ds_read_b128 v[182:185], v165 offset:3072
	s_add_u32 s36, s36, 0x40000
	s_addc_u32 s37, s37, 0
	s_mov_b32 m0, s52
	v_lshl_add_u64 v[220:221], s[36:37], 0, v[128:129]
	ds_read_b128 v[186:189], v163 offset:32768
	ds_read_b128 v[190:193], v163 offset:33792
	ds_read_b128 v[194:197], v163 offset:34816
	ds_read_b128 v[198:201], v163 offset:35840
	ds_read_b128 v[204:207], v163 offset:36864
	ds_read_b128 v[208:211], v163 offset:37888
	ds_read_b128 v[212:215], v163 offset:38912
	ds_read_b128 v[216:219], v163 offset:39936
	global_load_lds_dwordx4 v[220:221], off
	v_lshl_add_u64 v[220:221], s[36:37], 0, v[130:131]
	s_mov_b32 m0, s53
	s_nop 0
	global_load_lds_dwordx4 v[220:221], off
	ds_read_b128 v[220:223], v166
	ds_read_b128 v[224:227], v166 offset:1024
	ds_read_b128 v[228:231], v166 offset:2048
	ds_read_b128 v[232:235], v166 offset:3072
	s_waitcnt lgkmcnt(0)
	s_waitcnt vmcnt(8)
	s_barrier
	s_setprio 1
	v_mfma_f32_16x16x32_bf16 v[124:127], v[170:173], v[186:189], v[124:127]
	v_mfma_f32_16x16x32_bf16 v[120:123], v[178:181], v[186:189], v[120:123]
	v_mfma_f32_16x16x32_bf16 v[112:115], v[170:173], v[194:197], v[112:115]
	v_mfma_f32_16x16x32_bf16 v[104:107], v[178:181], v[194:197], v[104:107]
	v_mfma_f32_16x16x32_bf16 v[96:99], v[170:173], v[204:207], v[96:99]
	v_mfma_f32_16x16x32_bf16 v[88:91], v[178:181], v[204:207], v[88:91]
	v_mfma_f32_16x16x32_bf16 v[80:83], v[170:173], v[212:215], v[80:83]
	v_mfma_f32_16x16x32_bf16 v[72:75], v[178:181], v[212:215], v[72:75]
	v_mfma_f32_16x16x32_bf16 v[124:127], v[174:177], v[190:193], v[124:127]
	v_mfma_f32_16x16x32_bf16 v[120:123], v[182:185], v[190:193], v[120:123]
	v_mfma_f32_16x16x32_bf16 v[112:115], v[174:177], v[198:201], v[112:115]
	v_mfma_f32_16x16x32_bf16 v[104:107], v[182:185], v[198:201], v[104:107]
	v_mfma_f32_16x16x32_bf16 v[96:99], v[174:177], v[208:211], v[96:99]
	v_mfma_f32_16x16x32_bf16 v[88:91], v[182:185], v[208:211], v[88:91]
	v_mfma_f32_16x16x32_bf16 v[80:83], v[174:177], v[216:219], v[80:83]
	v_mfma_f32_16x16x32_bf16 v[72:75], v[182:185], v[216:219], v[72:75]
	v_mfma_f32_16x16x32_bf16 v[116:119], v[220:223], v[186:189], v[116:119]
	v_mfma_f32_16x16x32_bf16 v[108:111], v[228:231], v[186:189], v[108:111]
	v_mfma_f32_16x16x32_bf16 v[100:103], v[220:223], v[194:197], v[100:103]
	v_mfma_f32_16x16x32_bf16 v[92:95], v[228:231], v[194:197], v[92:95]
	v_mfma_f32_16x16x32_bf16 v[84:87], v[220:223], v[204:207], v[84:87]
	v_mfma_f32_16x16x32_bf16 v[76:79], v[228:231], v[204:207], v[76:79]
	v_mfma_f32_16x16x32_bf16 v[68:71], v[220:223], v[212:215], v[68:71]
	v_mfma_f32_16x16x32_bf16 v[64:67], v[228:231], v[212:215], v[64:67]
	v_mfma_f32_16x16x32_bf16 v[116:119], v[224:227], v[190:193], v[116:119]
	v_mfma_f32_16x16x32_bf16 v[108:111], v[232:235], v[190:193], v[108:111]
	v_mfma_f32_16x16x32_bf16 v[100:103], v[224:227], v[198:201], v[100:103]
	v_mfma_f32_16x16x32_bf16 v[92:95], v[232:235], v[198:201], v[92:95]
	v_mfma_f32_16x16x32_bf16 v[84:87], v[224:227], v[208:211], v[84:87]
	v_mfma_f32_16x16x32_bf16 v[76:79], v[232:235], v[208:211], v[76:79]
	v_mfma_f32_16x16x32_bf16 v[68:71], v[224:227], v[216:219], v[68:71]
	v_mfma_f32_16x16x32_bf16 v[64:67], v[232:235], v[216:219], v[64:67]
	s_setprio 0
	s_barrier
	ds_read_b128 v[186:189], v163 offset:49152
	ds_read_b128 v[190:193], v163 offset:50176
	ds_read_b128 v[194:197], v163 offset:51200
	ds_read_b128 v[198:201], v163 offset:52224
	ds_read_b128 v[204:207], v163 offset:53248
	ds_read_b128 v[208:211], v163 offset:54272
	ds_read_b128 v[212:215], v163 offset:55296
	ds_read_b128 v[216:219], v163 offset:56320
	s_mov_b32 m0, s54
	v_lshl_add_u64 v[144:145], v[144:145], 0, s[12:13]
	global_load_lds_dwordx4 v[144:145], off
	v_lshl_add_u64 v[144:145], v[236:237], 0, s[12:13]
	s_mov_b32 m0, s55
	s_nop 0
	global_load_lds_dwordx4 v[144:145], off
	s_mov_b32 m0, s56
	v_lshl_add_u64 v[144:145], v[238:239], 0, s[12:13]
	global_load_lds_dwordx4 v[144:145], off
	v_lshl_add_u64 v[144:145], v[240:241], 0, s[12:13]
	s_mov_b32 m0, s57
	s_nop 0
	global_load_lds_dwordx4 v[144:145], off
	s_add_u32 s34, s34, 0x40080
	s_addc_u32 s35, s35, 0
	s_mov_b32 m0, s58
	v_lshl_add_u64 v[144:145], s[34:35], 0, v[128:129]
	global_load_lds_dwordx4 v[144:145], off
	v_lshl_add_u64 v[144:145], s[34:35], 0, v[130:131]
	s_mov_b32 m0, s59
	s_nop 0
	global_load_lds_dwordx4 v[144:145], off
	s_waitcnt lgkmcnt(0)
	s_waitcnt vmcnt(8)
	s_barrier
	s_setprio 1
	v_mfma_f32_16x16x32_bf16 v[60:63], v[170:173], v[186:189], v[60:63]
	v_mfma_f32_16x16x32_bf16 v[56:59], v[178:181], v[186:189], v[56:59]
	v_mfma_f32_16x16x32_bf16 v[48:51], v[170:173], v[194:197], v[48:51]
	v_mfma_f32_16x16x32_bf16 v[40:43], v[178:181], v[194:197], v[40:43]
	v_mfma_f32_16x16x32_bf16 v[32:35], v[170:173], v[204:207], v[32:35]
	v_mfma_f32_16x16x32_bf16 v[24:27], v[178:181], v[204:207], v[24:27]
	v_mfma_f32_16x16x32_bf16 v[16:19], v[170:173], v[212:215], v[16:19]
	v_mfma_f32_16x16x32_bf16 v[8:11], v[178:181], v[212:215], v[8:11]
	v_mfma_f32_16x16x32_bf16 v[60:63], v[174:177], v[190:193], v[60:63]
	v_mfma_f32_16x16x32_bf16 v[56:59], v[182:185], v[190:193], v[56:59]
	v_mfma_f32_16x16x32_bf16 v[48:51], v[174:177], v[198:201], v[48:51]
	v_mfma_f32_16x16x32_bf16 v[40:43], v[182:185], v[198:201], v[40:43]
	v_mfma_f32_16x16x32_bf16 v[32:35], v[174:177], v[208:211], v[32:35]
	v_mfma_f32_16x16x32_bf16 v[24:27], v[182:185], v[208:211], v[24:27]
	v_mfma_f32_16x16x32_bf16 v[16:19], v[174:177], v[216:219], v[16:19]
	v_mfma_f32_16x16x32_bf16 v[8:11], v[182:185], v[216:219], v[8:11]
	v_mfma_f32_16x16x32_bf16 v[52:55], v[220:223], v[186:189], v[52:55]
	v_mfma_f32_16x16x32_bf16 v[44:47], v[228:231], v[186:189], v[44:47]
	v_mfma_f32_16x16x32_bf16 v[36:39], v[220:223], v[194:197], v[36:39]
	v_mfma_f32_16x16x32_bf16 v[28:31], v[228:231], v[194:197], v[28:31]
	v_mfma_f32_16x16x32_bf16 v[20:23], v[220:223], v[204:207], v[20:23]
	v_mfma_f32_16x16x32_bf16 v[12:15], v[228:231], v[204:207], v[12:15]
	v_mfma_f32_16x16x32_bf16 v[4:7], v[220:223], v[212:215], v[4:7]
	v_mfma_f32_16x16x32_bf16 v[0:3], v[228:231], v[212:215], v[0:3]
	v_mfma_f32_16x16x32_bf16 v[52:55], v[224:227], v[190:193], v[52:55]
	v_mfma_f32_16x16x32_bf16 v[44:47], v[232:235], v[190:193], v[44:47]
	v_mfma_f32_16x16x32_bf16 v[36:39], v[224:227], v[198:201], v[36:39]
	v_mfma_f32_16x16x32_bf16 v[28:31], v[232:235], v[198:201], v[28:31]
	v_mfma_f32_16x16x32_bf16 v[20:23], v[224:227], v[208:211], v[20:23]
	v_mfma_f32_16x16x32_bf16 v[12:15], v[232:235], v[208:211], v[12:15]
	v_mfma_f32_16x16x32_bf16 v[4:7], v[224:227], v[216:219], v[4:7]
	v_mfma_f32_16x16x32_bf16 v[0:3], v[232:235], v[216:219], v[0:3]
	s_setprio 0
	s_add_i32 s41, s41, 2
	s_add_u32 s30, s30, 0x100
	s_addc_u32 s31, s31, 0
	s_add_u32 s39, s39, 0x100
	s_addc_u32 s40, s40, 0
	s_cmp_gt_u32 s41, 13
	s_barrier

.LBB0_1335:
	s_xor_b64 s[14:15], s[22:23], -1
	s_and_b64 s[22:23], s[22:23], exec
	s_cselect_b32 s24, s11, s17
	s_cselect_b32 s25, s10, s16
	s_cselect_b32 s26, s13, s19
	s_cselect_b32 s27, s12, s18
	s_add_u32 s16, s16, 0xb0080
	s_addc_u32 s17, s17, 0
	s_add_u32 s52, s18, 0x100
	s_addc_u32 s53, s19, 0
	s_mov_b32 s54, -2
	s_waitcnt vmcnt(0)
	ds_read_b128 v[128:131], v162
	ds_read_b128 v[132:135], v162 offset:1024
	ds_read_b128 v[146:149], v162 offset:2048
	ds_read_b128 v[150:153], v162 offset:3072
	s_add_u32 s18, s16, 0xfff50080
	s_addc_u32 s19, s17, -1
	s_cmp_eq_u32 s54, 40
	s_cselect_b32 s23, s24, s19
	s_cselect_b32 s22, s25, s18
	s_cselect_b32 s19, s26, s53
	s_cselect_b32 s18, s27, s52
	v_lshl_add_u64 v[158:159], s[16:17], 0, v[140:141]
	s_add_i32 m0, s35, 0xc000
	ds_read_b128 v[154:157], v163
	ds_read_b128 v[168:171], v163 offset:1024
	ds_read_b128 v[172:175], v163 offset:2048
	ds_read_b128 v[176:179], v163 offset:3072
	ds_read_b128 v[180:183], v163 offset:4096
	ds_read_b128 v[184:187], v163 offset:5120
	ds_read_b128 v[188:191], v163 offset:6144
	ds_read_b128 v[192:195], v163 offset:7168
	global_load_lds_dwordx4 v[158:159], off
	v_lshl_add_u64 v[158:159], s[16:17], 0, v[142:143]
	s_add_i32 m0, s35, 0xe000
	s_nop 0
	global_load_lds_dwordx4 v[158:159], off
	ds_read_b128 v[196:199], v164
	ds_read_b128 v[200:203], v164 offset:1024
	ds_read_b128 v[204:207], v164 offset:2048
	ds_read_b128 v[208:211], v164 offset:3072
	s_waitcnt lgkmcnt(0)
	s_waitcnt vmcnt(8)
	s_barrier
	s_setprio 1
	v_mfma_f32_16x16x32_bf16 v[124:127], v[128:131], v[154:157], 0
	v_mfma_f32_16x16x32_bf16 v[120:123], v[146:149], v[154:157], 0
	v_mfma_f32_16x16x32_bf16 v[116:119], v[128:131], v[172:175], 0
	v_mfma_f32_16x16x32_bf16 v[112:115], v[146:149], v[172:175], 0
	v_mfma_f32_16x16x32_bf16 v[92:95], v[128:131], v[180:183], 0
	v_mfma_f32_16x16x32_bf16 v[88:91], v[146:149], v[180:183], 0
	v_mfma_f32_16x16x32_bf16 v[76:79], v[128:131], v[188:191], 0
	v_mfma_f32_16x16x32_bf16 v[72:75], v[146:149], v[188:191], 0
	v_mfma_f32_16x16x32_bf16 v[124:127], v[132:135], v[168:171], v[124:127]
	v_mfma_f32_16x16x32_bf16 v[120:123], v[150:153], v[168:171], v[120:123]
	v_mfma_f32_16x16x32_bf16 v[116:119], v[132:135], v[176:179], v[116:119]
	v_mfma_f32_16x16x32_bf16 v[112:115], v[150:153], v[176:179], v[112:115]
	v_mfma_f32_16x16x32_bf16 v[92:95], v[132:135], v[184:187], v[92:95]
	v_mfma_f32_16x16x32_bf16 v[88:91], v[150:153], v[184:187], v[88:91]
	v_mfma_f32_16x16x32_bf16 v[76:79], v[132:135], v[192:195], v[76:79]
	v_mfma_f32_16x16x32_bf16 v[72:75], v[150:153], v[192:195], v[72:75]
	v_mfma_f32_16x16x32_bf16 v[108:111], v[196:199], v[154:157], 0
	v_mfma_f32_16x16x32_bf16 v[104:107], v[204:207], v[154:157], 0
	v_mfma_f32_16x16x32_bf16 v[100:103], v[196:199], v[172:175], 0
	v_mfma_f32_16x16x32_bf16 v[96:99], v[204:207], v[172:175], 0
	v_mfma_f32_16x16x32_bf16 v[84:87], v[196:199], v[180:183], 0
	v_mfma_f32_16x16x32_bf16 v[80:83], v[204:207], v[180:183], 0
	v_mfma_f32_16x16x32_bf16 v[68:71], v[196:199], v[188:191], 0
	v_mfma_f32_16x16x32_bf16 v[64:67], v[204:207], v[188:191], 0
	v_mfma_f32_16x16x32_bf16 v[108:111], v[200:203], v[168:171], v[108:111]
	v_mfma_f32_16x16x32_bf16 v[104:107], v[208:211], v[168:171], v[104:107]
	v_mfma_f32_16x16x32_bf16 v[100:103], v[200:203], v[176:179], v[100:103]
	v_mfma_f32_16x16x32_bf16 v[96:99], v[208:211], v[176:179], v[96:99]
	v_mfma_f32_16x16x32_bf16 v[84:87], v[200:203], v[184:187], v[84:87]
	v_mfma_f32_16x16x32_bf16 v[80:83], v[208:211], v[184:187], v[80:83]
	v_mfma_f32_16x16x32_bf16 v[68:71], v[200:203], v[192:195], v[68:71]
	v_mfma_f32_16x16x32_bf16 v[64:67], v[208:211], v[192:195], v[64:67]
	s_setprio 0
	s_barrier
	ds_read_b128 v[154:157], v163 offset:16384
	ds_read_b128 v[168:171], v163 offset:17408
	ds_read_b128 v[172:175], v163 offset:18432
	ds_read_b128 v[176:179], v163 offset:19456
	ds_read_b128 v[180:183], v163 offset:20480
	ds_read_b128 v[184:187], v163 offset:21504
	ds_read_b128 v[188:191], v163 offset:22528
	ds_read_b128 v[192:195], v163 offset:23552
	s_mov_b32 m0, s33
	v_lshl_add_u64 v[158:159], s[18:19], 0, v[138:139]
	global_load_lds_dwordx4 v[158:159], off
	v_lshl_add_u64 v[212:213], s[18:19], 0, v[136:137]
	s_mov_b32 m0, s34
	s_nop 0
	global_load_lds_dwordx4 v[212:213], off
	s_mov_b32 m0, s35
	v_lshl_add_u64 v[214:215], s[22:23], 0, v[138:139]
	global_load_lds_dwordx4 v[214:215], off
	v_lshl_add_u64 v[216:217], s[22:23], 0, v[136:137]
	s_mov_b32 m0, s36
	s_nop 0
	global_load_lds_dwordx4 v[216:217], off
	s_add_u32 s56, s18, 0xb0000
	s_addc_u32 s57, s19, 0
	s_mov_b32 m0, s37
	v_lshl_add_u64 v[248:249], s[56:57], 0, v[138:139]
	global_load_lds_dwordx4 v[248:249], off
	v_lshl_add_u64 v[248:249], s[56:57], 0, v[136:137]
	s_mov_b32 m0, s38
	s_nop 0
	global_load_lds_dwordx4 v[248:249], off
	s_waitcnt lgkmcnt(0)
	s_waitcnt vmcnt(8)
	s_barrier
	s_setprio 1
	v_mfma_f32_16x16x32_bf16 v[60:63], v[128:131], v[154:157], 0
	v_mfma_f32_16x16x32_bf16 v[56:59], v[146:149], v[154:157], 0
	v_mfma_f32_16x16x32_bf16 v[44:47], v[128:131], v[172:175], 0
	v_mfma_f32_16x16x32_bf16 v[40:43], v[146:149], v[172:175], 0
	v_mfma_f32_16x16x32_bf16 v[28:31], v[128:131], v[180:183], 0
	v_mfma_f32_16x16x32_bf16 v[24:27], v[146:149], v[180:183], 0
	v_mfma_f32_16x16x32_bf16 v[12:15], v[128:131], v[188:191], 0
	v_mfma_f32_16x16x32_bf16 v[8:11], v[146:149], v[188:191], 0
	v_mfma_f32_16x16x32_bf16 v[60:63], v[132:135], v[168:171], v[60:63]
	v_mfma_f32_16x16x32_bf16 v[56:59], v[150:153], v[168:171], v[56:59]
	v_mfma_f32_16x16x32_bf16 v[44:47], v[132:135], v[176:179], v[44:47]
	v_mfma_f32_16x16x32_bf16 v[40:43], v[150:153], v[176:179], v[40:43]
	v_mfma_f32_16x16x32_bf16 v[28:31], v[132:135], v[184:187], v[28:31]
	v_mfma_f32_16x16x32_bf16 v[24:27], v[150:153], v[184:187], v[24:27]
	v_mfma_f32_16x16x32_bf16 v[12:15], v[132:135], v[192:195], v[12:15]
	v_mfma_f32_16x16x32_bf16 v[8:11], v[150:153], v[192:195], v[8:11]
	v_mfma_f32_16x16x32_bf16 v[52:55], v[196:199], v[154:157], 0
	v_mfma_f32_16x16x32_bf16 v[48:51], v[204:207], v[154:157], 0
	v_mfma_f32_16x16x32_bf16 v[36:39], v[196:199], v[172:175], 0
	v_mfma_f32_16x16x32_bf16 v[32:35], v[204:207], v[172:175], 0
	v_mfma_f32_16x16x32_bf16 v[20:23], v[196:199], v[180:183], 0
	v_mfma_f32_16x16x32_bf16 v[16:19], v[204:207], v[180:183], 0
	v_mfma_f32_16x16x32_bf16 v[4:7], v[196:199], v[188:191], 0
	v_mfma_f32_16x16x32_bf16 v[0:3], v[204:207], v[188:191], 0
	v_mfma_f32_16x16x32_bf16 v[52:55], v[200:203], v[168:171], v[52:55]
	v_mfma_f32_16x16x32_bf16 v[48:51], v[208:211], v[168:171], v[48:51]
	v_mfma_f32_16x16x32_bf16 v[36:39], v[200:203], v[176:179], v[36:39]
	v_mfma_f32_16x16x32_bf16 v[32:35], v[208:211], v[176:179], v[32:35]
	v_mfma_f32_16x16x32_bf16 v[20:23], v[200:203], v[184:187], v[20:23]
	v_mfma_f32_16x16x32_bf16 v[16:19], v[208:211], v[184:187], v[16:19]
	v_mfma_f32_16x16x32_bf16 v[4:7], v[200:203], v[192:195], v[4:7]
	v_mfma_f32_16x16x32_bf16 v[0:3], v[208:211], v[192:195], v[0:3]
	s_setprio 0
	s_barrier
	ds_read_b128 v[128:131], v165
	ds_read_b128 v[132:135], v165 offset:1024
	ds_read_b128 v[146:149], v165 offset:2048
	ds_read_b128 v[150:153], v165 offset:3072
	s_add_u32 s22, s22, 0xb0000
	s_addc_u32 s23, s23, 0
	s_mov_b32 m0, s39
	v_lshl_add_u64 v[196:197], s[22:23], 0, v[138:139]
	ds_read_b128 v[154:157], v163 offset:32768
	ds_read_b128 v[168:171], v163 offset:33792
	ds_read_b128 v[172:175], v163 offset:34816
	ds_read_b128 v[176:179], v163 offset:35840
	ds_read_b128 v[180:183], v163 offset:36864
	ds_read_b128 v[184:187], v163 offset:37888
	ds_read_b128 v[188:191], v163 offset:38912
	ds_read_b128 v[192:195], v163 offset:39936
	global_load_lds_dwordx4 v[196:197], off
	v_lshl_add_u64 v[196:197], s[22:23], 0, v[136:137]
	s_mov_b32 m0, s40
	s_nop 0
	global_load_lds_dwordx4 v[196:197], off
	ds_read_b128 v[196:199], v166
	ds_read_b128 v[200:203], v166 offset:1024
	ds_read_b128 v[204:207], v166 offset:2048
	ds_read_b128 v[208:211], v166 offset:3072
	s_waitcnt lgkmcnt(0)
	s_waitcnt vmcnt(8)
	s_barrier
	s_setprio 1
	v_mfma_f32_16x16x32_bf16 v[124:127], v[128:131], v[154:157], v[124:127]
	v_mfma_f32_16x16x32_bf16 v[120:123], v[146:149], v[154:157], v[120:123]
	v_mfma_f32_16x16x32_bf16 v[116:119], v[128:131], v[172:175], v[116:119]
	v_mfma_f32_16x16x32_bf16 v[112:115], v[146:149], v[172:175], v[112:115]
	v_mfma_f32_16x16x32_bf16 v[92:95], v[128:131], v[180:183], v[92:95]
	v_mfma_f32_16x16x32_bf16 v[88:91], v[146:149], v[180:183], v[88:91]
	v_mfma_f32_16x16x32_bf16 v[76:79], v[128:131], v[188:191], v[76:79]
	v_mfma_f32_16x16x32_bf16 v[72:75], v[146:149], v[188:191], v[72:75]
	v_mfma_f32_16x16x32_bf16 v[124:127], v[132:135], v[168:171], v[124:127]
	v_mfma_f32_16x16x32_bf16 v[120:123], v[150:153], v[168:171], v[120:123]
	v_mfma_f32_16x16x32_bf16 v[116:119], v[132:135], v[176:179], v[116:119]
	v_mfma_f32_16x16x32_bf16 v[112:115], v[150:153], v[176:179], v[112:115]
	v_mfma_f32_16x16x32_bf16 v[92:95], v[132:135], v[184:187], v[92:95]
	v_mfma_f32_16x16x32_bf16 v[88:91], v[150:153], v[184:187], v[88:91]
	v_mfma_f32_16x16x32_bf16 v[76:79], v[132:135], v[192:195], v[76:79]
	v_mfma_f32_16x16x32_bf16 v[72:75], v[150:153], v[192:195], v[72:75]
	v_mfma_f32_16x16x32_bf16 v[108:111], v[196:199], v[154:157], v[108:111]
	v_mfma_f32_16x16x32_bf16 v[104:107], v[204:207], v[154:157], v[104:107]
	v_mfma_f32_16x16x32_bf16 v[100:103], v[196:199], v[172:175], v[100:103]
	v_mfma_f32_16x16x32_bf16 v[96:99], v[204:207], v[172:175], v[96:99]
	v_mfma_f32_16x16x32_bf16 v[84:87], v[196:199], v[180:183], v[84:87]
	v_mfma_f32_16x16x32_bf16 v[80:83], v[204:207], v[180:183], v[80:83]
	v_mfma_f32_16x16x32_bf16 v[68:71], v[196:199], v[188:191], v[68:71]
	v_mfma_f32_16x16x32_bf16 v[64:67], v[204:207], v[188:191], v[64:67]
	v_mfma_f32_16x16x32_bf16 v[108:111], v[200:203], v[168:171], v[108:111]
	v_mfma_f32_16x16x32_bf16 v[104:107], v[208:211], v[168:171], v[104:107]
	v_mfma_f32_16x16x32_bf16 v[100:103], v[200:203], v[176:179], v[100:103]
	v_mfma_f32_16x16x32_bf16 v[96:99], v[208:211], v[176:179], v[96:99]
	v_mfma_f32_16x16x32_bf16 v[84:87], v[200:203], v[184:187], v[84:87]
	v_mfma_f32_16x16x32_bf16 v[80:83], v[208:211], v[184:187], v[80:83]
	v_mfma_f32_16x16x32_bf16 v[68:71], v[200:203], v[192:195], v[68:71]
	v_mfma_f32_16x16x32_bf16 v[64:67], v[208:211], v[192:195], v[64:67]
	s_setprio 0
	s_barrier
	ds_read_b128 v[154:157], v163 offset:49152
	ds_read_b128 v[168:171], v163 offset:50176
	ds_read_b128 v[172:175], v163 offset:51200
	ds_read_b128 v[176:179], v163 offset:52224
	ds_read_b128 v[180:183], v163 offset:53248
	ds_read_b128 v[184:187], v163 offset:54272
	ds_read_b128 v[188:191], v163 offset:55296
	ds_read_b128 v[192:195], v163 offset:56320
	s_mov_b32 m0, s41
	v_lshl_add_u64 v[158:159], v[158:159], 0, s[8:9]
	global_load_lds_dwordx4 v[158:159], off
	v_lshl_add_u64 v[158:159], v[212:213], 0, s[8:9]
	s_mov_b32 m0, s42
	s_nop 0
	global_load_lds_dwordx4 v[158:159], off
	s_mov_b32 m0, s43
	v_lshl_add_u64 v[158:159], v[214:215], 0, s[8:9]
	global_load_lds_dwordx4 v[158:159], off
	v_lshl_add_u64 v[158:159], v[216:217], 0, s[8:9]
	s_mov_b32 m0, s44
	s_nop 0
	global_load_lds_dwordx4 v[158:159], off
	s_add_u32 s18, s18, 0xb0080
	s_addc_u32 s19, s19, 0
	s_mov_b32 m0, s45
	v_lshl_add_u64 v[248:249], s[18:19], 0, v[138:139]
	global_load_lds_dwordx4 v[248:249], off
	v_lshl_add_u64 v[248:249], s[18:19], 0, v[136:137]
	s_mov_b32 m0, s46
	s_nop 0
	global_load_lds_dwordx4 v[248:249], off
	s_waitcnt lgkmcnt(0)
	s_waitcnt vmcnt(8)
	s_barrier
	s_setprio 1
	v_mfma_f32_16x16x32_bf16 v[60:63], v[128:131], v[154:157], v[60:63]
	v_mfma_f32_16x16x32_bf16 v[56:59], v[146:149], v[154:157], v[56:59]
	v_mfma_f32_16x16x32_bf16 v[44:47], v[128:131], v[172:175], v[44:47]
	v_mfma_f32_16x16x32_bf16 v[40:43], v[146:149], v[172:175], v[40:43]
	v_mfma_f32_16x16x32_bf16 v[28:31], v[128:131], v[180:183], v[28:31]
	v_mfma_f32_16x16x32_bf16 v[24:27], v[146:149], v[180:183], v[24:27]
	v_mfma_f32_16x16x32_bf16 v[12:15], v[128:131], v[188:191], v[12:15]
	v_mfma_f32_16x16x32_bf16 v[8:11], v[146:149], v[188:191], v[8:11]
	v_mfma_f32_16x16x32_bf16 v[60:63], v[132:135], v[168:171], v[60:63]
	v_mfma_f32_16x16x32_bf16 v[56:59], v[150:153], v[168:171], v[56:59]
	v_mfma_f32_16x16x32_bf16 v[44:47], v[132:135], v[176:179], v[44:47]
	v_mfma_f32_16x16x32_bf16 v[40:43], v[150:153], v[176:179], v[40:43]
	v_mfma_f32_16x16x32_bf16 v[28:31], v[132:135], v[184:187], v[28:31]
	v_mfma_f32_16x16x32_bf16 v[24:27], v[150:153], v[184:187], v[24:27]
	v_mfma_f32_16x16x32_bf16 v[12:15], v[132:135], v[192:195], v[12:15]
	v_mfma_f32_16x16x32_bf16 v[8:11], v[150:153], v[192:195], v[8:11]
	v_mfma_f32_16x16x32_bf16 v[52:55], v[196:199], v[154:157], v[52:55]
	v_mfma_f32_16x16x32_bf16 v[48:51], v[204:207], v[154:157], v[48:51]
	v_mfma_f32_16x16x32_bf16 v[36:39], v[196:199], v[172:175], v[36:39]
	v_mfma_f32_16x16x32_bf16 v[32:35], v[204:207], v[172:175], v[32:35]
	v_mfma_f32_16x16x32_bf16 v[20:23], v[196:199], v[180:183], v[20:23]
	v_mfma_f32_16x16x32_bf16 v[16:19], v[204:207], v[180:183], v[16:19]
	v_mfma_f32_16x16x32_bf16 v[4:7], v[196:199], v[188:191], v[4:7]
	v_mfma_f32_16x16x32_bf16 v[0:3], v[204:207], v[188:191], v[0:3]
	v_mfma_f32_16x16x32_bf16 v[52:55], v[200:203], v[168:171], v[52:55]
	v_mfma_f32_16x16x32_bf16 v[48:51], v[208:211], v[168:171], v[48:51]
	v_mfma_f32_16x16x32_bf16 v[36:39], v[200:203], v[176:179], v[36:39]
	v_mfma_f32_16x16x32_bf16 v[32:35], v[208:211], v[176:179], v[32:35]
	v_mfma_f32_16x16x32_bf16 v[20:23], v[200:203], v[184:187], v[20:23]
	v_mfma_f32_16x16x32_bf16 v[16:19], v[208:211], v[184:187], v[16:19]
	v_mfma_f32_16x16x32_bf16 v[4:7], v[200:203], v[192:195], v[4:7]
	v_mfma_f32_16x16x32_bf16 v[0:3], v[208:211], v[192:195], v[0:3]
	s_setprio 0
	s_add_i32 s54, s54, 2
	s_add_u32 s16, s16, 0x100
	s_addc_u32 s17, s17, 0
	s_add_u32 s52, s52, 0x100
	s_addc_u32 s53, s53, 0
	s_cmp_gt_u32 s54, 41
	s_barrier
